# M1->M2 and M2->M3 barriers without the L2 write-back: every cross-XCD M1/M2 result is stored write-through and drained before the arrival
# speedup vs baseline: 1.0055x; 1.0033x over previous
; #define LAS __attribute__((address_space(3)))
; __device__ __forceinline__ unsigned pk2(float lo, float hi) { return pg8::cvt_pk_bf16(lo, hi); }
; template <bool FULL> __device__ __forceinline__ void lru_tile(const Args& a, int l, int tile, LAS unsigned char* lds, int tid, int lane, int wave) {
;     ...
;         u32x4 w; w.x = pk2(xc[0], xc[1]); w.y = pk2(xc[2], xc[3]); w.z = pk2(xc[4], xc[5]); w.w = pk2(xc[6], xc[7]);
;         *(LAS u32x4*)(lds + OFF_XC + (t * 264 + c8 * 8) * 2) = w;
;     }
;     __syncthreads();
;     {
;         const int cb = wave & 3, chh = wave >> 2; const bf16* WA = (const bf16*)(wl + WL_WA); const bf16* WX = (const bf16*)(wl + WL_WX);
;         const float* c8t = (const float*)(a.ws + WS_TAB) + (size_t)l * 256;
;         f32x4 av[8], bv[8];
; #pragma unroll
;         for (int et = 0; et < 8; ++et) {
;             const int e0 = chh * 128 + et * 16, nb = e0 >> 6, el = e0 & 63;
;             f32x4 ra = {0.f, 0.f, 0.f, 0.f}, ia = {0.f, 0.f, 0.f, 0.f};
; #pragma unroll
;             for (int ks = 0; ks < 2; ++ks) {
;                 const bf16x8 xv = *(const LAS bf16x8*)(lds + OFF_XC + ((cb * 16 + fr) * 264 + nb * 64 + 32 * ks + 8 * fq) * 2);
;                 const bf16x8 wa = *(const bf16x8*)(WA + (size_t)nb * 4096 + (el + fr) * 64 + 32 * ks + 8 * fq);
;                 const bf16x8 wx = *(const bf16x8*)(WX + (size_t)nb * 4096 + (el + fr) * 64 + 32 * ks + 8 * fq);
;                 MFMA16(wa, xv, ra); MFMA16(wx, xv, ia);
;             }
;             const int c0 = e0 + 4 * fq;
;             const f32x4 ba = *(const f32x4*)(a.in[22] + (size_t)l * 256 + c0), bx = *(const f32x4*)(a.in[24] + (size_t)l * 256 + c0), c8v = *(const f32x4*)(c8t + c0);
;             const u32x2 xr = *(const LAS u32x2*)(lds + OFF_XC + ((cb * 16 + fr) * 264 + c0) * 2);
;             float lav[4];
;             const float xcv[4] = {__uint_as_float(xr.x << 16), __uint_as_float(xr.x & 0xffff0000u), __uint_as_float(xr.y << 16), __uint_as_float(xr.y & 0xffff0000u)};
; #pragma unroll
;             for (int r = 0; r < 4; ++r) {
;                 const float rg = sigmoidf_(ra[r] + ba[r]), ig = sigmoidf_(ia[r] + bx[r]);
;                 const float la = c8v[r] * rg; const float av_ = __expf(la); const float m2 = -expm1f(2.0f * la);
;                 av[et][r] = av_; bv[et][r] = sqrtf(fmaxf(m2, 0.f)) * ig * xcv[r]; lav[r] = la;
.LBB0_1323:
	s_or_b64 exec, exec, s[0:1]
	s_waitcnt vmcnt(0)
	v_cvt_pk_bf16_f32 v4, v4, v5
	v_cvt_pk_bf16_f32 v5, v6, v7
	v_cvt_pk_bf16_f32 v6, v0, v1
	v_mad_u64_u32 v[0:1], s[0:1], v9, s12, v[8:9]
	s_ashr_i32 s4, s7, 8
	s_add_i32 s0, 0, 0x10000
	s_lshl_b32 s24, s4, 1
	v_lshl_add_u32 v0, v0, 1, s0
	s_bfe_u32 s1, s7, 0x20006
	s_ashr_i32 s25, s24, 31
	v_cvt_pk_bf16_f32 v7, v2, v3
	ds_write_b128 v0, v[4:7]
	v_lshrrev_b32_e32 v0, 4, v66
	s_lshl_b32 s5, s4, 7
	s_lshl_b32 s7, s1, 4
	s_lshl_b64 s[24:25], s[24:25], 13
	v_or_b32_e32 v79, s7, v77
	v_lshlrev_b32_e32 v1, 3, v0
	v_lshlrev_b32_e32 v86, 2, v0
	v_or_b32_e32 v0, s7, v67
	s_add_u32 s40, s57, s24
	v_mad_u32_u24 v50, v79, s12, v1
	v_ashrrev_i32_e32 v1, 31, v0
	s_addc_u32 s41, s58, s25
	v_lshlrev_b64 v[0:1], 11, v[0:1]
	v_lshlrev_b32_e32 v144, 7, v77
	s_add_u32 s42, s59, s24
	v_lshl_add_u64 v[52:53], s[78:79], 0, v[0:1]
	v_add_u32_e32 v2, s5, v50
	v_lshl_add_u64 v[0:1], s[40:41], 0, v[144:145]
	v_and_b32_e32 v68, 48, v66
	v_mov_b32_e32 v69, v145
	s_addc_u32 s43, s60, s25
	v_lshl_add_u64 v[20:21], v[0:1], 0, v[68:69]
	v_lshl_add_u64 v[0:1], s[42:43], 0, v[144:145]
	v_lshl_add_u32 v38, v2, 1, s0
	s_waitcnt lgkmcnt(0)
	s_barrier
	global_load_dwordx4 v[118:121], v[20:21], off
	global_load_dwordx4 v[122:125], v[20:21], off offset:64
	global_load_dwordx4 v[126:129], v[20:21], off offset:2048
	global_load_dwordx4 v[130:133], v[20:21], off offset:2112
	v_lshl_add_u64 v[22:23], v[0:1], 0, v[68:69]
	global_load_dwordx4 v[134:137], v[22:23], off
	global_load_dwordx4 v[138:141], v[22:23], off offset:64
	global_load_dwordx4 v[150:153], v[22:23], off offset:2048
	ds_read_b128 v[0:3], v38
	ds_read_b128 v[12:15], v38 offset:64
	v_or_b32_e32 v54, s5, v86
	v_ashrrev_i32_e32 v55, 31, v54
	v_readlane_b32 s28, v254, 47
	v_readlane_b32 s29, v254, 48
	v_readlane_b32 s16, v254, 45
	v_readlane_b32 s30, v254, 49
	v_readlane_b32 s17, v254, 46
	v_readlane_b32 s31, v254, 50
	v_mad_u32_u24 v24, v79, s12, v54
	v_lshl_add_u32 v51, v24, 1, s0
	v_lshl_add_u64 v[48:49], v[54:55], 1, v[52:53]
	v_or_b32_e32 v60, 0x1000, v144
	v_mov_b32_e32 v61, v145
	v_mov_b32_e32 v71, v145
	s_or_b32 s7, s5, 64
	s_ashr_i32 s24, s7, 6
	s_ashr_i32 s25, s24, 31
	s_lshl_b64 s[24:25], s[24:25], 13
	s_add_u32 s26, s57, s24
	s_addc_u32 s27, s58, s25
	s_add_u32 s24, s59, s24
	s_addc_u32 s25, s60, s25
	s_waitcnt vmcnt(6) lgkmcnt(1)
	v_mfma_f32_16x16x32_bf16 v[4:7], v[118:121], v[0:3], 0
	s_waitcnt vmcnt(2)
	v_mfma_f32_16x16x32_bf16 v[0:3], v[134:137], v[0:3], 0
	ds_read_b64 v[24:25], v51
	s_waitcnt vmcnt(2) lgkmcnt(1)
	v_mfma_f32_16x16x32_bf16 v[8:11], v[122:125], v[12:15], v[4:7]
	s_waitcnt vmcnt(1)
	v_mfma_f32_16x16x32_bf16 v[4:7], v[138:141], v[12:15], v[0:3]
	s_nop 2
	v_lshlrev_b64 v[0:1], 2, v[54:55]
	v_lshl_add_u64 v[40:41], s[28:29], 0, v[0:1]
	global_load_dwordx4 v[16:19], v[40:41], off
	v_lshl_add_u64 v[44:45], s[16:17], 0, v[0:1]
	v_lshl_add_u64 v[46:47], s[30:31], 0, v[0:1]
	global_load_dwordx4 v[0:3], v[44:45], off
	global_load_dwordx4 v[118:121], v[46:47], off
	s_waitcnt vmcnt(2)
	v_add_f32_e32 v8, v8, v16
	v_add_f32_e32 v9, v9, v17
	v_mul_f32_e32 v8, 0xbfb8aa3b, v8
	v_mul_f32_e32 v9, 0xbfb8aa3b, v9
	v_exp_f32_e32 v8, v8
	v_exp_f32_e32 v9, v9
	s_waitcnt vmcnt(0)
	v_add_f32_e32 v4, v4, v118
	v_add_f32_e32 v5, v5, v119
	v_add_f32_e32 v8, 1.0, v8
	v_add_f32_e32 v9, 1.0, v9
	v_rcp_f32_e32 v8, v8
	v_rcp_f32_e32 v9, v9
	s_waitcnt lgkmcnt(0)
	v_lshlrev_b32_e32 v12, 16, v24
	v_and_b32_e32 v13, 0xffff0000, v24
	v_add_f32_e32 v10, v10, v18
	v_pk_mul_f32 v[8:9], v[0:1], v[8:9]
	v_add_f32_e32 v11, v11, v19
	v_pk_add_f32 v[16:17], v[8:9], v[8:9]
	v_mul_f32_e32 v10, 0xbfb8aa3b, v10
	v_mul_f32_e32 v1, 0x3fb8aa3b, v16
	v_rndne_f32_e32 v1, v1
	v_fmamk_f32 v24, v1, 0xbf317218, v16
	v_fmac_f32_e32 v24, 0x3102e308, v1
	v_fmamk_f32 v26, v24, 0x395133b1, v177
	v_cmp_eq_f32_e32 vcc, s2, v1
	v_cvt_i32_f32_e32 v1, v1
	v_fmaak_f32 v26, v24, v26, 0x3c0887f9
	v_fmaak_f32 v26, v24, v26, 0x3d2aaa81
	v_fmaak_f32 v26, v24, v26, 0x3e2aaaab
	v_fma_f32 v26, v24, v26, 0.5
	v_ldexp_f32 v1, 1.0, v1
	v_mul_f32_e32 v26, v24, v26
	v_cndmask_b32_e32 v1, v1, v195, vcc
	v_fmac_f32_e32 v24, v24, v26
	v_add_f32_e32 v26, -1.0, v1
	v_fmac_f32_e32 v26, v1, v24
	v_add_f32_e32 v1, v26, v26
	v_cndmask_b32_e32 v1, v26, v1, vcc
	v_max_f32_e64 v1, -v1, 0
	v_cmp_gt_f32_e32 vcc, s19, v1
	v_mul_f32_e32 v24, 0x4f800000, v1
	v_mul_f32_e32 v11, 0xbfb8aa3b, v11
	v_cndmask_b32_e32 v1, v1, v24, vcc
	v_sqrt_f32_e32 v24, v1
	v_exp_f32_e32 v10, v10
	v_exp_f32_e32 v11, v11
	v_mul_f32_e32 v4, 0xbfb8aa3b, v4
	v_add_u32_e32 v26, -1, v24
	v_fma_f32 v27, -v26, v24, v1
	v_cmp_ge_f32_e64 s[36:37], 0, v27
	v_add_u32_e32 v27, 1, v24
	v_mul_f32_e32 v5, 0xbfb8aa3b, v5
	v_cndmask_b32_e64 v26, v24, v26, s[36:37]
	v_fma_f32 v24, -v27, v24, v1
	v_cmp_lt_f32_e64 s[36:37], 0, v24
	v_exp_f32_e32 v4, v4
	v_exp_f32_e32 v5, v5
	v_cndmask_b32_e64 v24, v26, v27, s[36:37]
	v_mul_f32_e32 v26, 0x37800000, v24
	v_cndmask_b32_e32 v24, v24, v26, vcc
	v_cmp_class_f32_e32 vcc, v1, v178
	v_add_f32_e32 v10, 1.0, v10
	v_add_f32_e32 v11, 1.0, v11
	v_cndmask_b32_e32 v1, v24, v1, vcc
	v_mul_f32_e32 v24, 0x3fb8aa3b, v17
	v_rndne_f32_e32 v24, v24
	v_fmamk_f32 v26, v24, 0xbf317218, v17
	v_fmac_f32_e32 v26, 0x3102e308, v24
	v_fmamk_f32 v27, v26, 0x395133b1, v177
	v_cmp_eq_f32_e32 vcc, s2, v24
	v_cvt_i32_f32_e32 v24, v24
	v_fmaak_f32 v27, v26, v27, 0x3c0887f9
	v_fmaak_f32 v27, v26, v27, 0x3d2aaa81
	v_fmaak_f32 v27, v26, v27, 0x3e2aaaab
	v_fma_f32 v27, v26, v27, 0.5
	v_ldexp_f32 v24, 1.0, v24
	v_mul_f32_e32 v27, v26, v27
	v_cndmask_b32_e32 v24, v24, v195, vcc
	v_fmac_f32_e32 v26, v26, v27
	v_add_f32_e32 v27, -1.0, v24
	v_fmac_f32_e32 v27, v24, v26
; #define LAS __attribute__((address_space(3)))
; __device__ __forceinline__ unsigned pk2(float lo, float hi) { return pg8::cvt_pk_bf16(lo, hi); }
; __device__ __forceinline__ float sigmoidf_(float x) { return __builtin_amdgcn_rcpf(1.0f + __expf(-x)); }
; #define MFMA16(X, Y, ACC) ACC = __builtin_amdgcn_mfma_f32_16x16x32_bf16(X, Y, ACC, 0, 0, 0)
; template <bool FULL> __device__ __forceinline__ void lru_tile(const Args& a, int l, int tile, LAS unsigned char* lds, int tid, int lane, int wave) {
;     ...
;             for (int ks = 0; ks < 2; ++ks) {
;                 const bf16x8 xv = *(const LAS bf16x8*)(lds + OFF_XC + ((cb * 16 + fr) * 264 + nb * 64 + 32 * ks + 8 * fq) * 2);
;                 const bf16x8 wa = *(const bf16x8*)(WA + (size_t)nb * 4096 + (el + fr) * 64 + 32 * ks + 8 * fq);
;                 const bf16x8 wx = *(const bf16x8*)(WX + (size_t)nb * 4096 + (el + fr) * 64 + 32 * ks + 8 * fq);
;                 MFMA16(wa, xv, ra); MFMA16(wx, xv, ia);
;             }
;             const int c0 = e0 + 4 * fq;
;             const f32x4 ba = *(const f32x4*)(a.in[22] + (size_t)l * 256 + c0), bx = *(const f32x4*)(a.in[24] + (size_t)l * 256 + c0), c8v = *(const f32x4*)(c8t + c0);
;             const u32x2 xr = *(const LAS u32x2*)(lds + OFF_XC + ((cb * 16 + fr) * 264 + c0) * 2);
;             float lav[4];
;             const float xcv[4] = {__uint_as_float(xr.x << 16), __uint_as_float(xr.x & 0xffff0000u), __uint_as_float(xr.y << 16), __uint_as_float(xr.y & 0xffff0000u)};
; #pragma unroll
;             for (int r = 0; r < 4; ++r) {
;                 const float rg = sigmoidf_(ra[r] + ba[r]), ig = sigmoidf_(ia[r] + bx[r]);
;                 const float la = c8v[r] * rg; const float av_ = __expf(la); const float m2 = -expm1f(2.0f * la);
;                 av[et][r] = av_; bv[et][r] = sqrtf(fmaxf(m2, 0.f)) * ig * xcv[r]; lav[r] = la;
;             }
;             {
;               bf16* yr = Y + (size_t)(t0 + cb * 16 + fr) * DM + c0;
;               u32x2 wl_; wl_.x = pk2(lav[0], lav[1]); wl_.y = pk2(lav[2], lav[3]); *(u32x2*)(yr + 768) = wl_;
;               u32x2 wb_; wb_.x = pk2(bv[et][0], bv[et][1]); wb_.y = pk2(bv[et][2], bv[et][3]); *(u32x2*)(yr + 512) = wb_; }
	v_add_f32_e32 v24, v27, v27
	v_cndmask_b32_e32 v24, v27, v24, vcc
	v_max_f32_e64 v24, -v24, 0
	v_cmp_gt_f32_e32 vcc, s19, v24
	v_mul_f32_e32 v26, 0x4f800000, v24
	v_rcp_f32_e32 v10, v10
	v_cndmask_b32_e32 v24, v24, v26, vcc
	v_sqrt_f32_e32 v26, v24
	v_rcp_f32_e32 v11, v11
	v_add_f32_e32 v4, 1.0, v4
	v_add_f32_e32 v5, 1.0, v5
	v_add_u32_e32 v27, -1, v26
	v_fma_f32 v28, -v27, v26, v24
	v_cmp_ge_f32_e64 s[36:37], 0, v28
	v_add_u32_e32 v28, 1, v26
	v_rcp_f32_e32 v4, v4
	v_cndmask_b32_e64 v27, v26, v27, s[36:37]
	v_fma_f32 v26, -v28, v26, v24
	v_cmp_lt_f32_e64 s[36:37], 0, v26
	v_rcp_f32_e32 v5, v5
	v_pk_mul_f32 v[10:11], v[2:3], v[10:11]
	v_cndmask_b32_e64 v26, v27, v28, s[36:37]
	global_load_dwordx4 v[28:31], v[22:23], off offset:2112
	v_mul_f32_e32 v27, 0x37800000, v26
	v_cndmask_b32_e32 v26, v26, v27, vcc
	v_cmp_class_f32_e32 vcc, v24, v178
	v_add_f32_e32 v6, v6, v120
	v_add_f32_e32 v7, v7, v121
	v_cndmask_b32_e32 v24, v26, v24, vcc
	v_cmp_nlt_f32_e32 vcc, s86, v16
	v_pk_add_f32 v[14:15], v[10:11], v[10:11]
	v_mul_f32_e32 v6, 0xbfb8aa3b, v6
	v_cndmask_b32_e32 v1, 0, v1, vcc
	v_cmp_nlt_f32_e32 vcc, s86, v17
	v_mul_f32_e32 v3, 0x3fb8aa3b, v14
	v_rndne_f32_e32 v3, v3
	v_cndmask_b32_e32 v24, 0, v24, vcc
	v_cmp_ngt_f32_e32 vcc, s56, v17
	v_mul_f32_e32 v7, 0xbfb8aa3b, v7
	v_exp_f32_e32 v6, v6
	v_cndmask_b32_e32 v17, 1.0, v24, vcc
	v_cmp_ngt_f32_e32 vcc, s56, v16
	v_exp_f32_e32 v7, v7
	v_add_f32_e32 v6, 1.0, v6
	v_cndmask_b32_e32 v16, 1.0, v1, vcc
	v_pk_mul_f32 v[4:5], v[4:5], v[16:17]
	v_fmamk_f32 v16, v3, 0xbf317218, v14
	v_fmac_f32_e32 v16, 0x3102e308, v3
	v_fmamk_f32 v17, v16, 0x395133b1, v177
	v_cmp_eq_f32_e32 vcc, s2, v3
	v_cvt_i32_f32_e32 v3, v3
	v_fmaak_f32 v17, v16, v17, 0x3c0887f9
	v_fmaak_f32 v17, v16, v17, 0x3d2aaa81
	v_fmaak_f32 v17, v16, v17, 0x3e2aaaab
	v_fma_f32 v17, v16, v17, 0.5
	v_ldexp_f32 v3, 1.0, v3
	v_mul_f32_e32 v17, v16, v17
	v_cndmask_b32_e32 v3, v3, v195, vcc
	v_fmac_f32_e32 v16, v16, v17
	v_add_f32_e32 v17, -1.0, v3
	v_fmac_f32_e32 v17, v3, v16
	v_add_f32_e32 v3, v17, v17
	v_cndmask_b32_e32 v3, v17, v3, vcc
	v_max_f32_e64 v3, -v3, 0
	v_cmp_gt_f32_e32 vcc, s19, v3
	v_mul_f32_e32 v16, 0x4f800000, v3
	v_add_f32_e32 v7, 1.0, v7
	v_cndmask_b32_e32 v3, v3, v16, vcc
	v_sqrt_f32_e32 v16, v3
	v_rcp_f32_e32 v6, v6
	v_rcp_f32_e32 v7, v7
	v_mul_f32_e32 v0, 0x3fb8aa3b, v8
	v_add_u32_e32 v17, -1, v16
	v_fma_f32 v18, -v17, v16, v3
	v_cmp_ge_f32_e64 s[36:37], 0, v18
	v_add_u32_e32 v18, 1, v16
	v_pk_mul_f32 v[4:5], v[4:5], v[12:13]
	v_cndmask_b32_e64 v17, v16, v17, s[36:37]
	v_fma_f32 v16, -v18, v16, v3
	v_cmp_lt_f32_e64 s[36:37], 0, v16
	v_mul_f32_e32 v1, 0x3fb8aa3b, v9
	v_lshlrev_b32_e32 v12, 16, v25
	v_cndmask_b32_e64 v16, v17, v18, s[36:37]
	v_mul_f32_e32 v17, 0x37800000, v16
	v_cndmask_b32_e32 v16, v16, v17, vcc
	v_cmp_class_f32_e32 vcc, v3, v178
	v_and_b32_e32 v13, 0xffff0000, v25
	v_cvt_pk_bf16_f32 v8, v8, v9
	v_cvt_pk_bf16_f32 v9, v10, v11
	global_store_dwordx2 v[48:49], v[8:9], off offset:1536
	v_cndmask_b32_e32 v3, v16, v3, vcc
	v_mul_f32_e32 v16, 0x3fb8aa3b, v15
	v_rndne_f32_e32 v16, v16
	v_fmamk_f32 v17, v16, 0xbf317218, v15
	v_fmac_f32_e32 v17, 0x3102e308, v16
	v_fmamk_f32 v18, v17, 0x395133b1, v177
	v_cmp_eq_f32_e32 vcc, s2, v16
	v_cvt_i32_f32_e32 v16, v16
	v_fmaak_f32 v18, v17, v18, 0x3c0887f9
	v_fmaak_f32 v18, v17, v18, 0x3d2aaa81
	v_fmaak_f32 v18, v17, v18, 0x3e2aaaab
	v_fma_f32 v18, v17, v18, 0.5
	v_ldexp_f32 v16, 1.0, v16
	v_mul_f32_e32 v18, v17, v18
	v_cndmask_b32_e32 v16, v16, v195, vcc
	v_fmac_f32_e32 v17, v17, v18
	v_add_f32_e32 v18, -1.0, v16
	v_fmac_f32_e32 v18, v16, v17
	v_add_f32_e32 v16, v18, v18
	v_cndmask_b32_e32 v16, v18, v16, vcc
	v_max_f32_e64 v16, -v16, 0
	v_cmp_gt_f32_e32 vcc, s19, v16
	v_mul_f32_e32 v17, 0x4f800000, v16
	v_cvt_pk_bf16_f32 v8, v4, v5
	v_mul_f32_e32 v2, 0x3fb8aa3b, v10
	v_cndmask_b32_e32 v16, v16, v17, vcc
	v_sqrt_f32_e32 v17, v16
	v_exp_f32_e32 v0, v0
	v_exp_f32_e32 v1, v1
	v_exp_f32_e32 v2, v2
	v_add_u32_e32 v18, -1, v17
	v_fma_f32 v19, -v18, v17, v16
	v_cmp_ge_f32_e64 s[36:37], 0, v19
	v_add_u32_e32 v19, 1, v17
	s_nop 0
	v_cndmask_b32_e64 v18, v17, v18, s[36:37]
	v_fma_f32 v17, -v19, v17, v16
	v_cmp_lt_f32_e64 s[36:37], 0, v17
	s_nop 1
	v_cndmask_b32_e64 v17, v18, v19, s[36:37]
	v_mul_f32_e32 v18, 0x37800000, v17
	v_cndmask_b32_e32 v17, v17, v18, vcc
	v_cmp_class_f32_e32 vcc, v16, v178
	s_nop 1
	v_cndmask_b32_e32 v16, v17, v16, vcc
	v_cmp_nlt_f32_e32 vcc, s86, v14
	s_nop 1
	v_cndmask_b32_e32 v3, 0, v3, vcc
	v_cmp_nlt_f32_e32 vcc, s86, v15
	s_nop 1
	v_cndmask_b32_e32 v16, 0, v16, vcc
	v_cmp_ngt_f32_e32 vcc, s56, v15
	s_nop 1
	v_cndmask_b32_e32 v15, 1.0, v16, vcc
	v_cmp_ngt_f32_e32 vcc, s56, v14
	s_nop 1
	v_cndmask_b32_e32 v14, 1.0, v3, vcc
	v_pk_mul_f32 v[6:7], v[6:7], v[14:15]
	v_mul_f32_e32 v3, 0x3fb8aa3b, v11
	v_pk_mul_f32 v[6:7], v[6:7], v[12:13]
	v_exp_f32_e32 v3, v3
	v_cvt_pk_bf16_f32 v9, v6, v7
	global_store_dwordx2 v[48:49], v[8:9], off offset:1024
	ds_read_b128 v[8:11], v38
	s_waitcnt vmcnt(0) lgkmcnt(0)
	v_mfma_f32_16x16x32_bf16 v[12:15], v[126:129], v[8:11], 0
	s_waitcnt vmcnt(0)
	v_mfma_f32_16x16x32_bf16 v[8:11], v[150:153], v[8:11], 0
	ds_read_b128 v[16:19], v38 offset:64
	s_waitcnt vmcnt(0) lgkmcnt(0)
	v_mfma_f32_16x16x32_bf16 v[20:23], v[130:133], v[16:19], v[12:15]
	s_waitcnt vmcnt(0)
	v_mfma_f32_16x16x32_bf16 v[12:15], v[28:31], v[16:19], v[8:11]
	global_load_dwordx4 v[24:27], v[40:41], off offset:64
	global_load_dwordx4 v[16:19], v[46:47], off offset:64
	s_nop 0
	global_load_dwordx4 v[8:11], v[44:45], off offset:64
	ds_read_b64 v[28:29], v51 offset:32
	s_waitcnt vmcnt(2)
	v_add_f32_e32 v20, v20, v24
	s_waitcnt vmcnt(1)
; #define LAS __attribute__((address_space(3)))
; __device__ __forceinline__ unsigned pk2(float lo, float hi) { return pg8::cvt_pk_bf16(lo, hi); }
; __device__ __forceinline__ float sigmoidf_(float x) { return __builtin_amdgcn_rcpf(1.0f + __expf(-x)); }
; template <bool FULL> __device__ __forceinline__ void lru_tile(const Args& a, int l, int tile, LAS unsigned char* lds, int tid, int lane, int wave) {
;     ...
;             const f32x4 ba = *(const f32x4*)(a.in[22] + (size_t)l * 256 + c0), bx = *(const f32x4*)(a.in[24] + (size_t)l * 256 + c0), c8v = *(const f32x4*)(c8t + c0);
;             const u32x2 xr = *(const LAS u32x2*)(lds + OFF_XC + ((cb * 16 + fr) * 264 + c0) * 2);
;             float lav[4];
;             const float xcv[4] = {__uint_as_float(xr.x << 16), __uint_as_float(xr.x & 0xffff0000u), __uint_as_float(xr.y << 16), __uint_as_float(xr.y & 0xffff0000u)};
; #pragma unroll
;             for (int r = 0; r < 4; ++r) {
;                 const float rg = sigmoidf_(ra[r] + ba[r]), ig = sigmoidf_(ia[r] + bx[r]);
;                 const float la = c8v[r] * rg; const float av_ = __expf(la); const float m2 = -expm1f(2.0f * la);
;                 av[et][r] = av_; bv[et][r] = sqrtf(fmaxf(m2, 0.f)) * ig * xcv[r]; lav[r] = la;
;             }
;             {
;               bf16* yr = Y + (size_t)(t0 + cb * 16 + fr) * DM + c0;
;               u32x2 wl_; wl_.x = pk2(lav[0], lav[1]); wl_.y = pk2(lav[2], lav[3]); *(u32x2*)(yr + 768) = wl_;
;               u32x2 wb_; wb_.x = pk2(bv[et][0], bv[et][1]); wb_.y = pk2(bv[et][2], bv[et][3]); *(u32x2*)(yr + 512) = wb_; }
	v_add_f32_e32 v12, v12, v16
	v_add_f32_e32 v16, v21, v25
	v_mul_f32_e32 v20, 0xbfb8aa3b, v20
	v_mul_f32_e32 v16, 0xbfb8aa3b, v16
	v_exp_f32_e32 v20, v20
	v_exp_f32_e32 v16, v16
	v_add_f32_e32 v13, v13, v17
	s_waitcnt lgkmcnt(0)
	v_lshlrev_b32_e32 v24, 16, v28
	v_add_f32_e32 v20, 1.0, v20
	v_add_f32_e32 v16, 1.0, v16
	v_rcp_f32_e32 v20, v20
	v_rcp_f32_e32 v21, v16
	v_and_b32_e32 v25, 0xffff0000, v28
	v_mul_f32_e32 v12, 0xbfb8aa3b, v12
	v_mul_f32_e32 v13, 0xbfb8aa3b, v13
	s_waitcnt vmcnt(0)
	v_pk_mul_f32 v[16:17], v[8:9], v[20:21]
	v_exp_f32_e32 v12, v12
	v_pk_add_f32 v[20:21], v[16:17], v[16:17]
	v_exp_f32_e32 v13, v13
	v_mul_f32_e32 v9, 0x3fb8aa3b, v20
	v_rndne_f32_e32 v9, v9
	v_fmamk_f32 v28, v9, 0xbf317218, v20
	v_fmac_f32_e32 v28, 0x3102e308, v9
	v_fmamk_f32 v30, v28, 0x395133b1, v177
	v_cmp_eq_f32_e32 vcc, s2, v9
	v_cvt_i32_f32_e32 v9, v9
	v_fmaak_f32 v30, v28, v30, 0x3c0887f9
	v_fmaak_f32 v30, v28, v30, 0x3d2aaa81
	v_fmaak_f32 v30, v28, v30, 0x3e2aaaab
	v_fma_f32 v30, v28, v30, 0.5
	v_ldexp_f32 v9, 1.0, v9
	v_mul_f32_e32 v30, v28, v30
	v_cndmask_b32_e32 v9, v9, v195, vcc
	v_fmac_f32_e32 v28, v28, v30
	v_add_f32_e32 v30, -1.0, v9
	v_fmac_f32_e32 v30, v9, v28
	v_add_f32_e32 v9, v30, v30
	v_cndmask_b32_e32 v9, v30, v9, vcc
	v_max_f32_e64 v9, -v9, 0
	v_cmp_gt_f32_e32 vcc, s19, v9
	v_mul_f32_e32 v28, 0x4f800000, v9
	v_add_f32_e32 v12, 1.0, v12
	v_cndmask_b32_e32 v9, v9, v28, vcc
	v_sqrt_f32_e32 v28, v9
	v_add_f32_e32 v13, 1.0, v13
	v_rcp_f32_e32 v12, v12
	v_rcp_f32_e32 v13, v13
	v_add_u32_e32 v30, -1, v28
	v_fma_f32 v31, -v30, v28, v9
	v_cmp_ge_f32_e64 s[36:37], 0, v31
	v_add_u32_e32 v31, 1, v28
	v_add_f32_e32 v14, v14, v18
	v_cndmask_b32_e64 v30, v28, v30, s[36:37]
	v_fma_f32 v28, -v31, v28, v9
	v_cmp_lt_f32_e64 s[36:37], 0, v28
	v_add_f32_e32 v18, v23, v27
	v_mul_f32_e32 v18, 0xbfb8aa3b, v18
	v_cndmask_b32_e64 v28, v30, v31, s[36:37]
	v_mul_f32_e32 v30, 0x37800000, v28
	v_cndmask_b32_e32 v28, v28, v30, vcc
	v_cmp_class_f32_e32 vcc, v9, v178
	v_exp_f32_e32 v18, v18
	v_add_f32_e32 v15, v15, v19
	v_cndmask_b32_e32 v9, v28, v9, vcc
	v_mul_f32_e32 v28, 0x3fb8aa3b, v21
	v_rndne_f32_e32 v28, v28
	v_fmamk_f32 v30, v28, 0xbf317218, v21
	v_fmac_f32_e32 v30, 0x3102e308, v28
	v_fmamk_f32 v31, v30, 0x395133b1, v177
	v_cmp_eq_f32_e32 vcc, s2, v28
	v_cvt_i32_f32_e32 v28, v28
	v_fmaak_f32 v31, v30, v31, 0x3c0887f9
	v_fmaak_f32 v31, v30, v31, 0x3d2aaa81
	v_fmaak_f32 v31, v30, v31, 0x3e2aaaab
	v_fma_f32 v31, v30, v31, 0.5
	v_ldexp_f32 v28, 1.0, v28
	v_mul_f32_e32 v31, v30, v31
	v_cndmask_b32_e32 v28, v28, v195, vcc
	v_fmac_f32_e32 v30, v30, v31
	v_add_f32_e32 v31, -1.0, v28
	v_fmac_f32_e32 v31, v28, v30
	v_add_f32_e32 v28, v31, v31
	v_cndmask_b32_e32 v28, v31, v28, vcc
	v_max_f32_e64 v28, -v28, 0
	v_cmp_gt_f32_e32 vcc, s19, v28
	v_mul_f32_e32 v30, 0x4f800000, v28
	v_add_f32_e32 v18, 1.0, v18
	v_cndmask_b32_e32 v28, v28, v30, vcc
	v_sqrt_f32_e32 v30, v28
	v_mul_f32_e32 v14, 0xbfb8aa3b, v14
	v_mul_f32_e32 v15, 0xbfb8aa3b, v15
	v_exp_f32_e32 v14, v14
	v_add_u32_e32 v31, -1, v30
	v_fma_f32 v32, -v31, v30, v28
	v_cmp_ge_f32_e64 s[36:37], 0, v32
	v_add_u32_e32 v32, 1, v30
	v_exp_f32_e32 v15, v15
	v_cndmask_b32_e64 v31, v30, v31, s[36:37]
	v_fma_f32 v30, -v32, v30, v28
	v_cmp_lt_f32_e64 s[36:37], 0, v30
	v_add_f32_e32 v14, 1.0, v14
	v_add_f32_e32 v15, 1.0, v15
	v_cndmask_b32_e64 v30, v31, v32, s[36:37]
	v_mul_f32_e32 v31, 0x37800000, v30
	v_cndmask_b32_e32 v30, v30, v31, vcc
	v_cmp_class_f32_e32 vcc, v28, v178
	v_rcp_f32_e32 v14, v14
	v_rcp_f32_e32 v15, v15
	v_cndmask_b32_e32 v28, v30, v28, vcc
	v_cmp_nlt_f32_e32 vcc, s86, v20
	v_mul_f32_e32 v8, 0x3fb8aa3b, v16
	v_and_b32_e32 v19, 0xffff0000, v29
	v_cndmask_b32_e32 v9, 0, v9, vcc
	v_cmp_nlt_f32_e32 vcc, s86, v21
	v_cvt_pk_bf16_f32 v16, v16, v17
	v_exp_f32_e32 v8, v8
	s_nop 0
	v_cndmask_b32_e32 v28, 0, v28, vcc
	v_cmp_ngt_f32_e32 vcc, s56, v21
	s_nop 1
	v_cndmask_b32_e32 v21, 1.0, v28, vcc
	v_cmp_ngt_f32_e32 vcc, s56, v20
	s_nop 1
	v_cndmask_b32_e32 v20, 1.0, v9, vcc
	v_pk_mul_f32 v[12:13], v[12:13], v[20:21]
	v_add_f32_e32 v20, v22, v26
	v_mul_f32_e32 v20, 0xbfb8aa3b, v20
	v_exp_f32_e32 v20, v20
	v_rcp_f32_e32 v21, v18
	v_pk_mul_f32 v[12:13], v[12:13], v[24:25]
	v_mul_f32_e32 v9, 0x3fb8aa3b, v17
	v_add_f32_e32 v20, 1.0, v20
	v_rcp_f32_e32 v20, v20
	v_lshlrev_b32_e32 v18, 16, v29
	v_exp_f32_e32 v9, v9
	v_pk_mul_f32 v[20:21], v[10:11], v[20:21]
	s_nop 0
	v_pk_add_f32 v[22:23], v[20:21], v[20:21]
	v_cvt_pk_bf16_f32 v17, v20, v21
	global_store_dwordx2 v[48:49], v[16:17], off offset:1568
	v_mul_f32_e32 v11, 0x3fb8aa3b, v22
	v_rndne_f32_e32 v11, v11
	v_fmamk_f32 v24, v11, 0xbf317218, v22
	v_fmac_f32_e32 v24, 0x3102e308, v11
	v_fmamk_f32 v25, v24, 0x395133b1, v177
	v_cmp_eq_f32_e32 vcc, s2, v11
	v_cvt_i32_f32_e32 v11, v11
	v_fmaak_f32 v25, v24, v25, 0x3c0887f9
	v_fmaak_f32 v25, v24, v25, 0x3d2aaa81
	v_fmaak_f32 v25, v24, v25, 0x3e2aaaab
	v_fma_f32 v25, v24, v25, 0.5
	v_ldexp_f32 v11, 1.0, v11
	v_mul_f32_e32 v25, v24, v25
	v_cndmask_b32_e32 v11, v11, v195, vcc
	v_fmac_f32_e32 v24, v24, v25
	v_add_f32_e32 v25, -1.0, v11
	v_fmac_f32_e32 v25, v11, v24
	v_add_f32_e32 v11, v25, v25
	v_cndmask_b32_e32 v11, v25, v11, vcc
	v_max_f32_e64 v11, -v11, 0
	v_cmp_gt_f32_e32 vcc, s19, v11
	v_mul_f32_e32 v24, 0x4f800000, v11
	v_cvt_pk_bf16_f32 v16, v12, v13
	v_mul_f32_e32 v10, 0x3fb8aa3b, v20
	v_cndmask_b32_e32 v11, v11, v24, vcc
	v_sqrt_f32_e32 v24, v11
	v_exp_f32_e32 v10, v10
	v_add_u32_e32 v25, -1, v24
	v_fma_f32 v26, -v25, v24, v11
	v_cmp_ge_f32_e64 s[36:37], 0, v26
	v_add_u32_e32 v26, 1, v24
	s_nop 0
	v_cndmask_b32_e64 v25, v24, v25, s[36:37]
	v_fma_f32 v24, -v26, v24, v11
	v_cmp_lt_f32_e64 s[36:37], 0, v24
	s_nop 1
; #define LAS __attribute__((address_space(3)))
; __device__ __forceinline__ unsigned pk2(float lo, float hi) { return pg8::cvt_pk_bf16(lo, hi); }
; __device__ __forceinline__ float sigmoidf_(float x) { return __builtin_amdgcn_rcpf(1.0f + __expf(-x)); }
; #define MFMA16(X, Y, ACC) ACC = __builtin_amdgcn_mfma_f32_16x16x32_bf16(X, Y, ACC, 0, 0, 0)
; template <bool FULL> __device__ __forceinline__ void lru_tile(const Args& a, int l, int tile, LAS unsigned char* lds, int tid, int lane, int wave) {
;     ...
;             for (int ks = 0; ks < 2; ++ks) {
;                 const bf16x8 xv = *(const LAS bf16x8*)(lds + OFF_XC + ((cb * 16 + fr) * 264 + nb * 64 + 32 * ks + 8 * fq) * 2);
;                 const bf16x8 wa = *(const bf16x8*)(WA + (size_t)nb * 4096 + (el + fr) * 64 + 32 * ks + 8 * fq);
;                 const bf16x8 wx = *(const bf16x8*)(WX + (size_t)nb * 4096 + (el + fr) * 64 + 32 * ks + 8 * fq);
;                 MFMA16(wa, xv, ra); MFMA16(wx, xv, ia);
;             }
;             const int c0 = e0 + 4 * fq;
;             const f32x4 ba = *(const f32x4*)(a.in[22] + (size_t)l * 256 + c0), bx = *(const f32x4*)(a.in[24] + (size_t)l * 256 + c0), c8v = *(const f32x4*)(c8t + c0);
;             const u32x2 xr = *(const LAS u32x2*)(lds + OFF_XC + ((cb * 16 + fr) * 264 + c0) * 2);
;             float lav[4];
;             const float xcv[4] = {__uint_as_float(xr.x << 16), __uint_as_float(xr.x & 0xffff0000u), __uint_as_float(xr.y << 16), __uint_as_float(xr.y & 0xffff0000u)};
; #pragma unroll
;             for (int r = 0; r < 4; ++r) {
;                 const float rg = sigmoidf_(ra[r] + ba[r]), ig = sigmoidf_(ia[r] + bx[r]);
;                 const float la = c8v[r] * rg; const float av_ = __expf(la); const float m2 = -expm1f(2.0f * la);
;                 av[et][r] = av_; bv[et][r] = sqrtf(fmaxf(m2, 0.f)) * ig * xcv[r]; lav[r] = la;
;             }
;             {
;               bf16* yr = Y + (size_t)(t0 + cb * 16 + fr) * DM + c0;
;               u32x2 wl_; wl_.x = pk2(lav[0], lav[1]); wl_.y = pk2(lav[2], lav[3]); *(u32x2*)(yr + 768) = wl_;
;               u32x2 wb_; wb_.x = pk2(bv[et][0], bv[et][1]); wb_.y = pk2(bv[et][2], bv[et][3]); *(u32x2*)(yr + 512) = wb_; }
	v_cndmask_b32_e64 v24, v25, v26, s[36:37]
	v_mul_f32_e32 v25, 0x37800000, v24
	v_cndmask_b32_e32 v24, v24, v25, vcc
	v_cmp_class_f32_e32 vcc, v11, v178
	s_nop 1
	v_cndmask_b32_e32 v11, v24, v11, vcc
	v_mul_f32_e32 v24, 0x3fb8aa3b, v23
	v_rndne_f32_e32 v24, v24
	v_fmamk_f32 v25, v24, 0xbf317218, v23
	v_fmac_f32_e32 v25, 0x3102e308, v24
	v_fmamk_f32 v26, v25, 0x395133b1, v177
	v_cmp_eq_f32_e32 vcc, s2, v24
	v_cvt_i32_f32_e32 v24, v24
	v_fmaak_f32 v26, v25, v26, 0x3c0887f9
	v_fmaak_f32 v26, v25, v26, 0x3d2aaa81
	v_fmaak_f32 v26, v25, v26, 0x3e2aaaab
	v_fma_f32 v26, v25, v26, 0.5
	v_ldexp_f32 v24, 1.0, v24
	v_mul_f32_e32 v26, v25, v26
	v_cndmask_b32_e32 v24, v24, v195, vcc
	v_fmac_f32_e32 v25, v25, v26
	v_add_f32_e32 v26, -1.0, v24
	v_fmac_f32_e32 v26, v24, v25
	v_add_f32_e32 v24, v26, v26
	v_cndmask_b32_e32 v24, v26, v24, vcc
	v_max_f32_e64 v24, -v24, 0
	v_cmp_gt_f32_e32 vcc, s19, v24
	v_mul_f32_e32 v25, 0x4f800000, v24
	s_nop 0
	v_cndmask_b32_e32 v24, v24, v25, vcc
	v_sqrt_f32_e32 v25, v24
	s_nop 0
	v_add_u32_e32 v26, -1, v25
	v_fma_f32 v27, -v26, v25, v24
	v_cmp_ge_f32_e64 s[36:37], 0, v27
	v_add_u32_e32 v27, 1, v25
	s_nop 0
	v_cndmask_b32_e64 v26, v25, v26, s[36:37]
	v_fma_f32 v25, -v27, v25, v24
	v_cmp_lt_f32_e64 s[36:37], 0, v25
	s_nop 1
	v_cndmask_b32_e64 v25, v26, v27, s[36:37]
	v_mul_f32_e32 v26, 0x37800000, v25
	v_cndmask_b32_e32 v25, v25, v26, vcc
	v_cmp_class_f32_e32 vcc, v24, v178
	s_nop 1
	v_cndmask_b32_e32 v24, v25, v24, vcc
	v_cmp_nlt_f32_e32 vcc, s86, v22
	s_nop 1
	v_cndmask_b32_e32 v11, 0, v11, vcc
	v_cmp_nlt_f32_e32 vcc, s86, v23
	s_nop 1
	v_cndmask_b32_e32 v24, 0, v24, vcc
	v_cmp_ngt_f32_e32 vcc, s56, v23
	s_nop 1
	v_cndmask_b32_e32 v23, 1.0, v24, vcc
	v_cmp_ngt_f32_e32 vcc, s56, v22
	s_nop 1
	v_cndmask_b32_e32 v22, 1.0, v11, vcc
	v_pk_mul_f32 v[14:15], v[14:15], v[22:23]
	v_mul_f32_e32 v11, 0x3fb8aa3b, v21
	v_pk_mul_f32 v[14:15], v[14:15], v[18:19]
	v_exp_f32_e32 v11, v11
	v_cvt_pk_bf16_f32 v17, v14, v15
	global_store_dwordx2 v[48:49], v[16:17], off offset:1056
	v_lshl_add_u64 v[16:17], s[40:41], 0, v[60:61]
	v_lshl_add_u64 v[28:29], v[16:17], 0, v[68:69]
	global_load_dwordx4 v[118:121], v[28:29], off
	global_load_dwordx4 v[122:125], v[28:29], off offset:64
	v_lshl_add_u64 v[16:17], s[42:43], 0, v[60:61]
	v_lshl_add_u64 v[32:33], v[16:17], 0, v[68:69]
	global_load_dwordx4 v[126:129], v[32:33], off
	global_load_dwordx4 v[130:133], v[32:33], off offset:64
	ds_read_b128 v[16:19], v38
	s_waitcnt vmcnt(3) lgkmcnt(0)
	v_mfma_f32_16x16x32_bf16 v[20:23], v[118:121], v[16:19], 0
	s_waitcnt vmcnt(1)
	v_mfma_f32_16x16x32_bf16 v[16:19], v[126:129], v[16:19], 0
	ds_read_b128 v[24:27], v38 offset:64
	s_nop 0
	s_waitcnt vmcnt(1) lgkmcnt(0)
	v_mfma_f32_16x16x32_bf16 v[28:31], v[122:125], v[24:27], v[20:23]
	s_waitcnt vmcnt(0)
	v_mfma_f32_16x16x32_bf16 v[20:23], v[130:133], v[24:27], v[16:19]
	global_load_dwordx4 v[32:35], v[40:41], off offset:128
	global_load_dwordx4 v[24:27], v[46:47], off offset:128
	s_nop 0
	global_load_dwordx4 v[16:19], v[44:45], off offset:128
	ds_read_b64 v[36:37], v51 offset:64
	s_waitcnt vmcnt(2)
	v_add_f32_e32 v28, v28, v32
	s_waitcnt vmcnt(1)
	v_add_f32_e32 v20, v20, v24
	v_add_f32_e32 v24, v29, v33
	v_mul_f32_e32 v28, 0xbfb8aa3b, v28
	v_mul_f32_e32 v24, 0xbfb8aa3b, v24
	v_exp_f32_e32 v28, v28
	v_exp_f32_e32 v24, v24
	v_add_f32_e32 v21, v21, v25
	s_waitcnt lgkmcnt(0)
	v_lshlrev_b32_e32 v32, 16, v36
	v_add_f32_e32 v28, 1.0, v28
	v_add_f32_e32 v24, 1.0, v24
	v_rcp_f32_e32 v28, v28
	v_rcp_f32_e32 v29, v24
	v_and_b32_e32 v33, 0xffff0000, v36
	v_mul_f32_e32 v20, 0xbfb8aa3b, v20
	v_mul_f32_e32 v21, 0xbfb8aa3b, v21
	s_waitcnt vmcnt(0)
	v_pk_mul_f32 v[24:25], v[16:17], v[28:29]
	v_exp_f32_e32 v20, v20
	v_pk_add_f32 v[28:29], v[24:25], v[24:25]
	v_exp_f32_e32 v21, v21
	v_mul_f32_e32 v17, 0x3fb8aa3b, v28
	v_rndne_f32_e32 v17, v17
	v_fmamk_f32 v36, v17, 0xbf317218, v28
	v_fmac_f32_e32 v36, 0x3102e308, v17
	v_fmamk_f32 v39, v36, 0x395133b1, v177
	v_cmp_eq_f32_e32 vcc, s2, v17
	v_cvt_i32_f32_e32 v17, v17
	v_fmaak_f32 v39, v36, v39, 0x3c0887f9
	v_fmaak_f32 v39, v36, v39, 0x3d2aaa81
	v_fmaak_f32 v39, v36, v39, 0x3e2aaaab
	v_fma_f32 v39, v36, v39, 0.5
	v_ldexp_f32 v17, 1.0, v17
	v_mul_f32_e32 v39, v36, v39
	v_cndmask_b32_e32 v17, v17, v195, vcc
	v_fmac_f32_e32 v36, v36, v39
	v_add_f32_e32 v39, -1.0, v17
	v_fmac_f32_e32 v39, v17, v36
	v_add_f32_e32 v17, v39, v39
	v_cndmask_b32_e32 v17, v39, v17, vcc
	v_max_f32_e64 v17, -v17, 0
	v_cmp_gt_f32_e32 vcc, s19, v17
	v_mul_f32_e32 v36, 0x4f800000, v17
	v_add_f32_e32 v20, 1.0, v20
	v_cndmask_b32_e32 v17, v17, v36, vcc
	v_sqrt_f32_e32 v36, v17
	v_add_f32_e32 v21, 1.0, v21
	v_rcp_f32_e32 v20, v20
	v_rcp_f32_e32 v21, v21
	v_add_u32_e32 v39, -1, v36
	v_fma_f32 v42, -v39, v36, v17
	v_cmp_ge_f32_e64 s[36:37], 0, v42
	v_add_u32_e32 v42, 1, v36
	v_add_f32_e32 v22, v22, v26
	v_cndmask_b32_e64 v39, v36, v39, s[36:37]
	v_fma_f32 v36, -v42, v36, v17
	v_cmp_lt_f32_e64 s[36:37], 0, v36
	v_add_f32_e32 v26, v31, v35
	v_mul_f32_e32 v26, 0xbfb8aa3b, v26
	v_cndmask_b32_e64 v36, v39, v42, s[36:37]
	v_mul_f32_e32 v39, 0x37800000, v36
	v_cndmask_b32_e32 v36, v36, v39, vcc
	v_cmp_class_f32_e32 vcc, v17, v178
	v_exp_f32_e32 v26, v26
	v_add_f32_e32 v23, v23, v27
	v_cndmask_b32_e32 v17, v36, v17, vcc
	v_mul_f32_e32 v36, 0x3fb8aa3b, v29
	v_rndne_f32_e32 v36, v36
	v_fmamk_f32 v39, v36, 0xbf317218, v29
	v_fmac_f32_e32 v39, 0x3102e308, v36
	v_fmamk_f32 v42, v39, 0x395133b1, v177
	v_cmp_eq_f32_e32 vcc, s2, v36
	v_cvt_i32_f32_e32 v36, v36
	v_fmaak_f32 v42, v39, v42, 0x3c0887f9
	v_fmaak_f32 v42, v39, v42, 0x3d2aaa81
	v_fmaak_f32 v42, v39, v42, 0x3e2aaaab
	v_fma_f32 v42, v39, v42, 0.5
	v_ldexp_f32 v36, 1.0, v36
; #define LAS __attribute__((address_space(3)))
; __device__ __forceinline__ unsigned pk2(float lo, float hi) { return pg8::cvt_pk_bf16(lo, hi); }
; __device__ __forceinline__ float sigmoidf_(float x) { return __builtin_amdgcn_rcpf(1.0f + __expf(-x)); }
; #define MFMA16(X, Y, ACC) ACC = __builtin_amdgcn_mfma_f32_16x16x32_bf16(X, Y, ACC, 0, 0, 0)
; template <bool FULL> __device__ __forceinline__ void lru_tile(const Args& a, int l, int tile, LAS unsigned char* lds, int tid, int lane, int wave) {
;     ...
;             for (int ks = 0; ks < 2; ++ks) {
;                 const bf16x8 xv = *(const LAS bf16x8*)(lds + OFF_XC + ((cb * 16 + fr) * 264 + nb * 64 + 32 * ks + 8 * fq) * 2);
;                 const bf16x8 wa = *(const bf16x8*)(WA + (size_t)nb * 4096 + (el + fr) * 64 + 32 * ks + 8 * fq);
;                 const bf16x8 wx = *(const bf16x8*)(WX + (size_t)nb * 4096 + (el + fr) * 64 + 32 * ks + 8 * fq);
;                 MFMA16(wa, xv, ra); MFMA16(wx, xv, ia);
;             }
;             const int c0 = e0 + 4 * fq;
;             const f32x4 ba = *(const f32x4*)(a.in[22] + (size_t)l * 256 + c0), bx = *(const f32x4*)(a.in[24] + (size_t)l * 256 + c0), c8v = *(const f32x4*)(c8t + c0);
;             const u32x2 xr = *(const LAS u32x2*)(lds + OFF_XC + ((cb * 16 + fr) * 264 + c0) * 2);
;             float lav[4];
;             const float xcv[4] = {__uint_as_float(xr.x << 16), __uint_as_float(xr.x & 0xffff0000u), __uint_as_float(xr.y << 16), __uint_as_float(xr.y & 0xffff0000u)};
; #pragma unroll
;             for (int r = 0; r < 4; ++r) {
;                 const float rg = sigmoidf_(ra[r] + ba[r]), ig = sigmoidf_(ia[r] + bx[r]);
;                 const float la = c8v[r] * rg; const float av_ = __expf(la); const float m2 = -expm1f(2.0f * la);
;                 av[et][r] = av_; bv[et][r] = sqrtf(fmaxf(m2, 0.f)) * ig * xcv[r]; lav[r] = la;
;             }
;             {
;               bf16* yr = Y + (size_t)(t0 + cb * 16 + fr) * DM + c0;
;               u32x2 wl_; wl_.x = pk2(lav[0], lav[1]); wl_.y = pk2(lav[2], lav[3]); *(u32x2*)(yr + 768) = wl_;
;               u32x2 wb_; wb_.x = pk2(bv[et][0], bv[et][1]); wb_.y = pk2(bv[et][2], bv[et][3]); *(u32x2*)(yr + 512) = wb_; }
	v_mul_f32_e32 v42, v39, v42
	v_cndmask_b32_e32 v36, v36, v195, vcc
	v_fmac_f32_e32 v39, v39, v42
	v_add_f32_e32 v42, -1.0, v36
	v_fmac_f32_e32 v42, v36, v39
	v_add_f32_e32 v36, v42, v42
	v_cndmask_b32_e32 v36, v42, v36, vcc
	v_max_f32_e64 v36, -v36, 0
	v_cmp_gt_f32_e32 vcc, s19, v36
	v_mul_f32_e32 v39, 0x4f800000, v36
	v_add_f32_e32 v26, 1.0, v26
	v_cndmask_b32_e32 v36, v36, v39, vcc
	v_sqrt_f32_e32 v39, v36
	v_mul_f32_e32 v22, 0xbfb8aa3b, v22
	v_mul_f32_e32 v23, 0xbfb8aa3b, v23
	v_exp_f32_e32 v22, v22
	v_add_u32_e32 v42, -1, v39
	v_fma_f32 v43, -v42, v39, v36
	v_cmp_ge_f32_e64 s[36:37], 0, v43
	v_add_u32_e32 v43, 1, v39
	v_exp_f32_e32 v23, v23
	v_cndmask_b32_e64 v42, v39, v42, s[36:37]
	v_fma_f32 v39, -v43, v39, v36
	v_cmp_lt_f32_e64 s[36:37], 0, v39
	v_add_f32_e32 v22, 1.0, v22
	v_add_f32_e32 v23, 1.0, v23
	v_cndmask_b32_e64 v39, v42, v43, s[36:37]
	v_mul_f32_e32 v42, 0x37800000, v39
	v_cndmask_b32_e32 v39, v39, v42, vcc
	v_cmp_class_f32_e32 vcc, v36, v178
	v_rcp_f32_e32 v22, v22
	v_rcp_f32_e32 v23, v23
	v_cndmask_b32_e32 v36, v39, v36, vcc
	v_cmp_nlt_f32_e32 vcc, s86, v28
	v_mul_f32_e32 v16, 0x3fb8aa3b, v24
	v_cvt_pk_bf16_f32 v24, v24, v25
	v_and_b32_e32 v27, 0xffff0000, v37
	v_cndmask_b32_e32 v17, 0, v17, vcc
	v_cmp_nlt_f32_e32 vcc, s86, v29
	v_exp_f32_e32 v16, v16
	s_nop 0
	v_cndmask_b32_e32 v36, 0, v36, vcc
	v_cmp_ngt_f32_e32 vcc, s56, v29
	s_nop 1
	v_cndmask_b32_e32 v29, 1.0, v36, vcc
	v_cmp_ngt_f32_e32 vcc, s56, v28
	s_nop 1
	v_cndmask_b32_e32 v28, 1.0, v17, vcc
	v_pk_mul_f32 v[20:21], v[20:21], v[28:29]
	v_add_f32_e32 v28, v30, v34
	v_mul_f32_e32 v28, 0xbfb8aa3b, v28
	v_exp_f32_e32 v28, v28
	v_rcp_f32_e32 v29, v26
	v_pk_mul_f32 v[20:21], v[20:21], v[32:33]
	v_mul_f32_e32 v17, 0x3fb8aa3b, v25
	v_add_f32_e32 v28, 1.0, v28
	v_rcp_f32_e32 v28, v28
	v_lshlrev_b32_e32 v26, 16, v37
	v_exp_f32_e32 v17, v17
	v_pk_mul_f32 v[28:29], v[18:19], v[28:29]
	s_nop 0
	v_pk_add_f32 v[30:31], v[28:29], v[28:29]
	v_cvt_pk_bf16_f32 v25, v28, v29
	global_store_dwordx2 v[48:49], v[24:25], off offset:1600
	v_mul_f32_e32 v19, 0x3fb8aa3b, v30
	v_rndne_f32_e32 v19, v19
	v_fmamk_f32 v32, v19, 0xbf317218, v30
	v_fmac_f32_e32 v32, 0x3102e308, v19
	v_fmamk_f32 v33, v32, 0x395133b1, v177
	v_cmp_eq_f32_e32 vcc, s2, v19
	v_cvt_i32_f32_e32 v19, v19
	v_fmaak_f32 v33, v32, v33, 0x3c0887f9
	v_fmaak_f32 v33, v32, v33, 0x3d2aaa81
	v_fmaak_f32 v33, v32, v33, 0x3e2aaaab
	v_fma_f32 v33, v32, v33, 0.5
	v_ldexp_f32 v19, 1.0, v19
	v_mul_f32_e32 v33, v32, v33
	v_cndmask_b32_e32 v19, v19, v195, vcc
	v_fmac_f32_e32 v32, v32, v33
	v_add_f32_e32 v33, -1.0, v19
	v_fmac_f32_e32 v33, v19, v32
	v_add_f32_e32 v19, v33, v33
	v_cndmask_b32_e32 v19, v33, v19, vcc
	v_max_f32_e64 v19, -v19, 0
	v_cmp_gt_f32_e32 vcc, s19, v19
	v_mul_f32_e32 v32, 0x4f800000, v19
	v_cvt_pk_bf16_f32 v24, v20, v21
	v_mul_f32_e32 v18, 0x3fb8aa3b, v28
	v_cndmask_b32_e32 v19, v19, v32, vcc
	v_sqrt_f32_e32 v32, v19
	v_exp_f32_e32 v18, v18
	v_add_u32_e32 v33, -1, v32
	v_fma_f32 v34, -v33, v32, v19
	v_cmp_ge_f32_e64 s[36:37], 0, v34
	v_add_u32_e32 v34, 1, v32
	s_nop 0
	v_cndmask_b32_e64 v33, v32, v33, s[36:37]
	v_fma_f32 v32, -v34, v32, v19
	v_cmp_lt_f32_e64 s[36:37], 0, v32
	s_nop 1
	v_cndmask_b32_e64 v32, v33, v34, s[36:37]
	v_mul_f32_e32 v33, 0x37800000, v32
	v_cndmask_b32_e32 v32, v32, v33, vcc
	v_cmp_class_f32_e32 vcc, v19, v178
	s_nop 1
	v_cndmask_b32_e32 v19, v32, v19, vcc
	v_mul_f32_e32 v32, 0x3fb8aa3b, v31
	v_rndne_f32_e32 v32, v32
	v_fmamk_f32 v33, v32, 0xbf317218, v31
	v_fmac_f32_e32 v33, 0x3102e308, v32
	v_fmamk_f32 v34, v33, 0x395133b1, v177
	v_cmp_eq_f32_e32 vcc, s2, v32
	v_cvt_i32_f32_e32 v32, v32
	v_fmaak_f32 v34, v33, v34, 0x3c0887f9
	v_fmaak_f32 v34, v33, v34, 0x3d2aaa81
	v_fmaak_f32 v34, v33, v34, 0x3e2aaaab
	v_fma_f32 v34, v33, v34, 0.5
	v_ldexp_f32 v32, 1.0, v32
	v_mul_f32_e32 v34, v33, v34
	v_cndmask_b32_e32 v32, v32, v195, vcc
	v_fmac_f32_e32 v33, v33, v34
	v_add_f32_e32 v34, -1.0, v32
	v_fmac_f32_e32 v34, v32, v33
	v_add_f32_e32 v32, v34, v34
	v_cndmask_b32_e32 v32, v34, v32, vcc
	v_max_f32_e64 v32, -v32, 0
	v_cmp_gt_f32_e32 vcc, s19, v32
	v_mul_f32_e32 v33, 0x4f800000, v32
	s_nop 0
	v_cndmask_b32_e32 v32, v32, v33, vcc
	v_sqrt_f32_e32 v33, v32
	s_nop 0
	v_add_u32_e32 v34, -1, v33
	v_fma_f32 v35, -v34, v33, v32
	v_cmp_ge_f32_e64 s[36:37], 0, v35
	v_add_u32_e32 v35, 1, v33
	s_nop 0
	v_cndmask_b32_e64 v34, v33, v34, s[36:37]
	v_fma_f32 v33, -v35, v33, v32
	v_cmp_lt_f32_e64 s[36:37], 0, v33
	s_nop 1
	v_cndmask_b32_e64 v33, v34, v35, s[36:37]
	v_mul_f32_e32 v34, 0x37800000, v33
	v_cndmask_b32_e32 v33, v33, v34, vcc
	v_cmp_class_f32_e32 vcc, v32, v178
	s_nop 1
	v_cndmask_b32_e32 v32, v33, v32, vcc
	v_cmp_nlt_f32_e32 vcc, s86, v30
	s_nop 1
	v_cndmask_b32_e32 v19, 0, v19, vcc
	v_cmp_nlt_f32_e32 vcc, s86, v31
	s_nop 1
	v_cndmask_b32_e32 v32, 0, v32, vcc
	v_cmp_ngt_f32_e32 vcc, s56, v31
	s_nop 1
	v_cndmask_b32_e32 v31, 1.0, v32, vcc
	v_cmp_ngt_f32_e32 vcc, s56, v30
	s_nop 1
	v_cndmask_b32_e32 v30, 1.0, v19, vcc
	v_pk_mul_f32 v[22:23], v[22:23], v[30:31]
	v_mul_f32_e32 v19, 0x3fb8aa3b, v29
	v_pk_mul_f32 v[22:23], v[22:23], v[26:27]
	v_exp_f32_e32 v19, v19
	v_cvt_pk_bf16_f32 v25, v22, v23
	global_store_dwordx2 v[48:49], v[24:25], off offset:1088
	v_mov_b32_e32 v24, 0x1800
	v_lshl_or_b32 v70, v66, 7, v24
	v_lshl_add_u64 v[24:25], s[40:41], 0, v[70:71]
	v_lshl_add_u64 v[36:37], v[24:25], 0, v[68:69]
	global_load_dwordx4 v[118:121], v[36:37], off
	global_load_dwordx4 v[122:125], v[36:37], off offset:64
	v_lshl_add_u64 v[24:25], s[42:43], 0, v[70:71]
	v_lshl_add_u64 v[42:43], v[24:25], 0, v[68:69]
	global_load_dwordx4 v[126:129], v[42:43], off
	global_load_dwordx4 v[56:59], v[42:43], off offset:64
	ds_read_b128 v[24:27], v38
	s_waitcnt vmcnt(3) lgkmcnt(0)
; #define LAS __attribute__((address_space(3)))
; __device__ __forceinline__ unsigned pk2(float lo, float hi) { return pg8::cvt_pk_bf16(lo, hi); }
; __device__ __forceinline__ float sigmoidf_(float x) { return __builtin_amdgcn_rcpf(1.0f + __expf(-x)); }
; template <bool FULL> __device__ __forceinline__ void lru_tile(const Args& a, int l, int tile, LAS unsigned char* lds, int tid, int lane, int wave) {
;     ...
;         for (int et = 0; et < 8; ++et) {
;             const int e0 = chh * 128 + et * 16, nb = e0 >> 6, el = e0 & 63;
;             f32x4 ra = {0.f, 0.f, 0.f, 0.f}, ia = {0.f, 0.f, 0.f, 0.f};
; #pragma unroll
;             for (int ks = 0; ks < 2; ++ks) {
;                 const bf16x8 xv = *(const LAS bf16x8*)(lds + OFF_XC + ((cb * 16 + fr) * 264 + nb * 64 + 32 * ks + 8 * fq) * 2);
;                 const bf16x8 wa = *(const bf16x8*)(WA + (size_t)nb * 4096 + (el + fr) * 64 + 32 * ks + 8 * fq);
;                 const bf16x8 wx = *(const bf16x8*)(WX + (size_t)nb * 4096 + (el + fr) * 64 + 32 * ks + 8 * fq);
;                 MFMA16(wa, xv, ra); MFMA16(wx, xv, ia);
;             }
;             const int c0 = e0 + 4 * fq;
;             const f32x4 ba = *(const f32x4*)(a.in[22] + (size_t)l * 256 + c0), bx = *(const f32x4*)(a.in[24] + (size_t)l * 256 + c0), c8v = *(const f32x4*)(c8t + c0);
;             const u32x2 xr = *(const LAS u32x2*)(lds + OFF_XC + ((cb * 16 + fr) * 264 + c0) * 2);
;             float lav[4];
;             const float xcv[4] = {__uint_as_float(xr.x << 16), __uint_as_float(xr.x & 0xffff0000u), __uint_as_float(xr.y << 16), __uint_as_float(xr.y & 0xffff0000u)};
; #pragma unroll
;             for (int r = 0; r < 4; ++r) {
;                 const float rg = sigmoidf_(ra[r] + ba[r]), ig = sigmoidf_(ia[r] + bx[r]);
;                 const float la = c8v[r] * rg; const float av_ = __expf(la); const float m2 = -expm1f(2.0f * la);
;                 av[et][r] = av_; bv[et][r] = sqrtf(fmaxf(m2, 0.f)) * ig * xcv[r]; lav[r] = la;
;             }
;             {
;               bf16* yr = Y + (size_t)(t0 + cb * 16 + fr) * DM + c0;
;               u32x2 wl_; wl_.x = pk2(lav[0], lav[1]); wl_.y = pk2(lav[2], lav[3]); *(u32x2*)(yr + 768) = wl_;
;               u32x2 wb_; wb_.x = pk2(bv[et][0], bv[et][1]); wb_.y = pk2(bv[et][2], bv[et][3]); *(u32x2*)(yr + 512) = wb_; }
	v_mfma_f32_16x16x32_bf16 v[28:31], v[118:121], v[24:27], 0
	s_waitcnt vmcnt(1)
	v_mfma_f32_16x16x32_bf16 v[24:27], v[126:129], v[24:27], 0
	ds_read_b128 v[32:35], v38 offset:64
	s_nop 0
	global_load_dwordx4 v[40:43], v[40:41], off offset:192
	s_waitcnt vmcnt(2) lgkmcnt(0)
	v_mfma_f32_16x16x32_bf16 v[36:39], v[122:125], v[32:35], v[28:31]
	s_waitcnt vmcnt(1)
	v_mfma_f32_16x16x32_bf16 v[28:31], v[56:59], v[32:35], v[24:27]
	s_nop 0
	global_load_dwordx4 v[32:35], v[46:47], off offset:192
	global_load_dwordx4 v[24:27], v[44:45], off offset:192
	ds_read_b64 v[44:45], v51 offset:96
	v_or_b32_e32 v56, s7, v86
	v_mad_u32_u24 v56, v79, s12, v56
	v_lshl_add_u32 v56, v56, 1, s0
	s_waitcnt vmcnt(2)
	v_add_f32_e32 v36, v36, v40
	s_waitcnt vmcnt(1)
	v_add_f32_e32 v28, v28, v32
	v_add_f32_e32 v32, v37, v41
	v_mul_f32_e32 v36, 0xbfb8aa3b, v36
	v_mul_f32_e32 v32, 0xbfb8aa3b, v32
	v_exp_f32_e32 v36, v36
	v_exp_f32_e32 v32, v32
	v_add_f32_e32 v29, v29, v33
	s_waitcnt lgkmcnt(0)
	v_lshlrev_b32_e32 v40, 16, v44
	v_add_f32_e32 v36, 1.0, v36
	v_add_f32_e32 v32, 1.0, v32
	v_rcp_f32_e32 v36, v36
	v_rcp_f32_e32 v37, v32
	v_and_b32_e32 v41, 0xffff0000, v44
	v_mul_f32_e32 v28, 0xbfb8aa3b, v28
	v_mul_f32_e32 v29, 0xbfb8aa3b, v29
	s_waitcnt vmcnt(0)
	v_pk_mul_f32 v[32:33], v[24:25], v[36:37]
	v_exp_f32_e32 v28, v28
	v_pk_add_f32 v[36:37], v[32:33], v[32:33]
	v_exp_f32_e32 v29, v29
	v_mul_f32_e32 v25, 0x3fb8aa3b, v36
	v_rndne_f32_e32 v25, v25
	v_fmamk_f32 v44, v25, 0xbf317218, v36
	v_fmac_f32_e32 v44, 0x3102e308, v25
	v_fmamk_f32 v46, v44, 0x395133b1, v177
	v_cmp_eq_f32_e32 vcc, s2, v25
	v_cvt_i32_f32_e32 v25, v25
	v_fmaak_f32 v46, v44, v46, 0x3c0887f9
	v_fmaak_f32 v46, v44, v46, 0x3d2aaa81
	v_fmaak_f32 v46, v44, v46, 0x3e2aaaab
	v_fma_f32 v46, v44, v46, 0.5
	v_ldexp_f32 v25, 1.0, v25
	v_mul_f32_e32 v46, v44, v46
	v_cndmask_b32_e32 v25, v25, v195, vcc
	v_fmac_f32_e32 v44, v44, v46
	v_add_f32_e32 v46, -1.0, v25
	v_fmac_f32_e32 v46, v25, v44
	v_add_f32_e32 v25, v46, v46
	v_cndmask_b32_e32 v25, v46, v25, vcc
	v_max_f32_e64 v25, -v25, 0
	v_cmp_gt_f32_e32 vcc, s19, v25
	v_mul_f32_e32 v44, 0x4f800000, v25
	v_add_f32_e32 v28, 1.0, v28
	v_cndmask_b32_e32 v25, v25, v44, vcc
	v_sqrt_f32_e32 v44, v25
	v_add_f32_e32 v29, 1.0, v29
	v_rcp_f32_e32 v28, v28
	v_rcp_f32_e32 v29, v29
	v_add_u32_e32 v46, -1, v44
	v_fma_f32 v47, -v46, v44, v25
	v_cmp_ge_f32_e64 s[36:37], 0, v47
	v_add_u32_e32 v47, 1, v44
	v_add_f32_e32 v30, v30, v34
	v_cndmask_b32_e64 v46, v44, v46, s[36:37]
	v_fma_f32 v44, -v47, v44, v25
	v_cmp_lt_f32_e64 s[36:37], 0, v44
	v_add_f32_e32 v34, v39, v43
	v_mul_f32_e32 v34, 0xbfb8aa3b, v34
	v_cndmask_b32_e64 v44, v46, v47, s[36:37]
	v_mul_f32_e32 v46, 0x37800000, v44
	v_cndmask_b32_e32 v44, v44, v46, vcc
	v_cmp_class_f32_e32 vcc, v25, v178
	v_exp_f32_e32 v34, v34
	v_add_f32_e32 v31, v31, v35
	v_cndmask_b32_e32 v25, v44, v25, vcc
	v_mul_f32_e32 v44, 0x3fb8aa3b, v37
	v_rndne_f32_e32 v44, v44
	v_fmamk_f32 v46, v44, 0xbf317218, v37
	v_fmac_f32_e32 v46, 0x3102e308, v44
	v_fmamk_f32 v47, v46, 0x395133b1, v177
	v_cmp_eq_f32_e32 vcc, s2, v44
	v_cvt_i32_f32_e32 v44, v44
	v_fmaak_f32 v47, v46, v47, 0x3c0887f9
	v_fmaak_f32 v47, v46, v47, 0x3d2aaa81
	v_fmaak_f32 v47, v46, v47, 0x3e2aaaab
	v_fma_f32 v47, v46, v47, 0.5
	v_ldexp_f32 v44, 1.0, v44
	v_mul_f32_e32 v47, v46, v47
	v_cndmask_b32_e32 v44, v44, v195, vcc
	v_fmac_f32_e32 v46, v46, v47
	v_add_f32_e32 v47, -1.0, v44
	v_fmac_f32_e32 v47, v44, v46
	v_add_f32_e32 v44, v47, v47
	v_cndmask_b32_e32 v44, v47, v44, vcc
	v_max_f32_e64 v44, -v44, 0
	v_cmp_gt_f32_e32 vcc, s19, v44
	v_mul_f32_e32 v46, 0x4f800000, v44
	v_add_f32_e32 v34, 1.0, v34
	v_cndmask_b32_e32 v44, v44, v46, vcc
	v_sqrt_f32_e32 v46, v44
	v_mul_f32_e32 v30, 0xbfb8aa3b, v30
	v_mul_f32_e32 v31, 0xbfb8aa3b, v31
	v_exp_f32_e32 v30, v30
	v_add_u32_e32 v47, -1, v46
	v_fma_f32 v51, -v47, v46, v44
	v_cmp_ge_f32_e64 s[36:37], 0, v51
	v_add_u32_e32 v51, 1, v46
	v_exp_f32_e32 v31, v31
	v_cndmask_b32_e64 v47, v46, v47, s[36:37]
	v_fma_f32 v46, -v51, v46, v44
	v_cmp_lt_f32_e64 s[36:37], 0, v46
	v_add_f32_e32 v30, 1.0, v30
	v_add_f32_e32 v31, 1.0, v31
	v_cndmask_b32_e64 v46, v47, v51, s[36:37]
	v_mul_f32_e32 v47, 0x37800000, v46
	v_cndmask_b32_e32 v46, v46, v47, vcc
	v_cmp_class_f32_e32 vcc, v44, v178
	v_rcp_f32_e32 v30, v30
	v_rcp_f32_e32 v31, v31
	v_cndmask_b32_e32 v44, v46, v44, vcc
	v_cmp_nlt_f32_e32 vcc, s86, v36
	v_mul_f32_e32 v24, 0x3fb8aa3b, v32
	v_and_b32_e32 v35, 0xffff0000, v45
	v_cndmask_b32_e32 v25, 0, v25, vcc
	v_cmp_nlt_f32_e32 vcc, s86, v37
	v_cvt_pk_bf16_f32 v32, v32, v33
	v_exp_f32_e32 v24, v24
	s_nop 0
	v_cndmask_b32_e32 v44, 0, v44, vcc
	v_cmp_ngt_f32_e32 vcc, s56, v37
	s_nop 1
	v_cndmask_b32_e32 v37, 1.0, v44, vcc
	v_cmp_ngt_f32_e32 vcc, s56, v36
	s_nop 1
	v_cndmask_b32_e32 v36, 1.0, v25, vcc
	v_pk_mul_f32 v[28:29], v[28:29], v[36:37]
	v_add_f32_e32 v36, v38, v42
	v_mul_f32_e32 v36, 0xbfb8aa3b, v36
	v_exp_f32_e32 v36, v36
	v_rcp_f32_e32 v37, v34
	v_pk_mul_f32 v[28:29], v[28:29], v[40:41]
	v_mul_f32_e32 v25, 0x3fb8aa3b, v33
	v_add_f32_e32 v36, 1.0, v36
	v_rcp_f32_e32 v36, v36
	v_lshlrev_b32_e32 v34, 16, v45
	v_exp_f32_e32 v25, v25
	v_pk_mul_f32 v[36:37], v[26:27], v[36:37]
	s_nop 0
	v_pk_add_f32 v[38:39], v[36:37], v[36:37]
	v_cvt_pk_bf16_f32 v33, v36, v37
	global_store_dwordx2 v[48:49], v[32:33], off offset:1632
	v_mul_f32_e32 v27, 0x3fb8aa3b, v38
	v_rndne_f32_e32 v27, v27
	v_fmamk_f32 v40, v27, 0xbf317218, v38
	v_fmac_f32_e32 v40, 0x3102e308, v27
	v_fmamk_f32 v41, v40, 0x395133b1, v177
	v_cmp_eq_f32_e32 vcc, s2, v27
	v_cvt_i32_f32_e32 v27, v27
	v_fmaak_f32 v41, v40, v41, 0x3c0887f9
	v_fmaak_f32 v41, v40, v41, 0x3d2aaa81
	v_fmaak_f32 v41, v40, v41, 0x3e2aaaab
; #define LAS __attribute__((address_space(3)))
; __device__ __forceinline__ unsigned pk2(float lo, float hi) { return pg8::cvt_pk_bf16(lo, hi); }
; __device__ __forceinline__ float sigmoidf_(float x) { return __builtin_amdgcn_rcpf(1.0f + __expf(-x)); }
; template <bool FULL> __device__ __forceinline__ void lru_tile(const Args& a, int l, int tile, LAS unsigned char* lds, int tid, int lane, int wave) {
;     ...
;         for (int et = 0; et < 8; ++et) {
;             const int e0 = chh * 128 + et * 16, nb = e0 >> 6, el = e0 & 63;
;             f32x4 ra = {0.f, 0.f, 0.f, 0.f}, ia = {0.f, 0.f, 0.f, 0.f};
; #pragma unroll
;             for (int ks = 0; ks < 2; ++ks) {
;                 const bf16x8 xv = *(const LAS bf16x8*)(lds + OFF_XC + ((cb * 16 + fr) * 264 + nb * 64 + 32 * ks + 8 * fq) * 2);
;                 const bf16x8 wa = *(const bf16x8*)(WA + (size_t)nb * 4096 + (el + fr) * 64 + 32 * ks + 8 * fq);
;                 const bf16x8 wx = *(const bf16x8*)(WX + (size_t)nb * 4096 + (el + fr) * 64 + 32 * ks + 8 * fq);
;                 MFMA16(wa, xv, ra); MFMA16(wx, xv, ia);
;             }
;             const int c0 = e0 + 4 * fq;
;             const f32x4 ba = *(const f32x4*)(a.in[22] + (size_t)l * 256 + c0), bx = *(const f32x4*)(a.in[24] + (size_t)l * 256 + c0), c8v = *(const f32x4*)(c8t + c0);
;             const u32x2 xr = *(const LAS u32x2*)(lds + OFF_XC + ((cb * 16 + fr) * 264 + c0) * 2);
;             float lav[4];
;             const float xcv[4] = {__uint_as_float(xr.x << 16), __uint_as_float(xr.x & 0xffff0000u), __uint_as_float(xr.y << 16), __uint_as_float(xr.y & 0xffff0000u)};
; #pragma unroll
;             for (int r = 0; r < 4; ++r) {
;                 const float rg = sigmoidf_(ra[r] + ba[r]), ig = sigmoidf_(ia[r] + bx[r]);
;                 const float la = c8v[r] * rg; const float av_ = __expf(la); const float m2 = -expm1f(2.0f * la);
;                 av[et][r] = av_; bv[et][r] = sqrtf(fmaxf(m2, 0.f)) * ig * xcv[r]; lav[r] = la;
;             }
;             {
;               bf16* yr = Y + (size_t)(t0 + cb * 16 + fr) * DM + c0;
;               u32x2 wl_; wl_.x = pk2(lav[0], lav[1]); wl_.y = pk2(lav[2], lav[3]); *(u32x2*)(yr + 768) = wl_;
;               u32x2 wb_; wb_.x = pk2(bv[et][0], bv[et][1]); wb_.y = pk2(bv[et][2], bv[et][3]); *(u32x2*)(yr + 512) = wb_; }
	v_fma_f32 v41, v40, v41, 0.5
	v_ldexp_f32 v27, 1.0, v27
	v_mul_f32_e32 v41, v40, v41
	v_cndmask_b32_e32 v27, v27, v195, vcc
	v_fmac_f32_e32 v40, v40, v41
	v_add_f32_e32 v41, -1.0, v27
	v_fmac_f32_e32 v41, v27, v40
	v_add_f32_e32 v27, v41, v41
	v_cndmask_b32_e32 v27, v41, v27, vcc
	v_max_f32_e64 v27, -v27, 0
	v_cmp_gt_f32_e32 vcc, s19, v27
	v_mul_f32_e32 v40, 0x4f800000, v27
	v_cvt_pk_bf16_f32 v32, v28, v29
	v_mul_f32_e32 v26, 0x3fb8aa3b, v36
	v_cndmask_b32_e32 v27, v27, v40, vcc
	v_sqrt_f32_e32 v40, v27
	v_exp_f32_e32 v26, v26
	v_add_u32_e32 v41, -1, v40
	v_fma_f32 v42, -v41, v40, v27
	v_cmp_ge_f32_e64 s[36:37], 0, v42
	v_add_u32_e32 v42, 1, v40
	s_nop 0
	v_cndmask_b32_e64 v41, v40, v41, s[36:37]
	v_fma_f32 v40, -v42, v40, v27
	v_cmp_lt_f32_e64 s[36:37], 0, v40
	s_nop 1
	v_cndmask_b32_e64 v40, v41, v42, s[36:37]
	v_mul_f32_e32 v41, 0x37800000, v40
	v_cndmask_b32_e32 v40, v40, v41, vcc
	v_cmp_class_f32_e32 vcc, v27, v178
	s_nop 1
	v_cndmask_b32_e32 v27, v40, v27, vcc
	v_mul_f32_e32 v40, 0x3fb8aa3b, v39
	v_rndne_f32_e32 v40, v40
	v_fmamk_f32 v41, v40, 0xbf317218, v39
	v_fmac_f32_e32 v41, 0x3102e308, v40
	v_fmamk_f32 v42, v41, 0x395133b1, v177
	v_cmp_eq_f32_e32 vcc, s2, v40
	v_cvt_i32_f32_e32 v40, v40
	v_fmaak_f32 v42, v41, v42, 0x3c0887f9
	v_fmaak_f32 v42, v41, v42, 0x3d2aaa81
	v_fmaak_f32 v42, v41, v42, 0x3e2aaaab
	v_fma_f32 v42, v41, v42, 0.5
	v_ldexp_f32 v40, 1.0, v40
	v_mul_f32_e32 v42, v41, v42
	v_cndmask_b32_e32 v40, v40, v195, vcc
	v_fmac_f32_e32 v41, v41, v42
	v_add_f32_e32 v42, -1.0, v40
	v_fmac_f32_e32 v42, v40, v41
	v_add_f32_e32 v40, v42, v42
	v_cndmask_b32_e32 v40, v42, v40, vcc
	v_max_f32_e64 v40, -v40, 0
	v_cmp_gt_f32_e32 vcc, s19, v40
	v_mul_f32_e32 v41, 0x4f800000, v40
	s_nop 0
	v_cndmask_b32_e32 v40, v40, v41, vcc
	v_sqrt_f32_e32 v41, v40
	s_nop 0
	v_add_u32_e32 v42, -1, v41
	v_fma_f32 v43, -v42, v41, v40
	v_cmp_ge_f32_e64 s[36:37], 0, v43
	v_add_u32_e32 v43, 1, v41
	s_nop 0
	v_cndmask_b32_e64 v42, v41, v42, s[36:37]
	v_fma_f32 v41, -v43, v41, v40
	v_cmp_lt_f32_e64 s[36:37], 0, v41
	s_nop 1
	v_cndmask_b32_e64 v41, v42, v43, s[36:37]
	v_mul_f32_e32 v42, 0x37800000, v41
	v_cndmask_b32_e32 v41, v41, v42, vcc
	v_cmp_class_f32_e32 vcc, v40, v178
	s_nop 1
	v_cndmask_b32_e32 v40, v41, v40, vcc
	v_cmp_nlt_f32_e32 vcc, s86, v38
	s_nop 1
	v_cndmask_b32_e32 v27, 0, v27, vcc
	v_cmp_nlt_f32_e32 vcc, s86, v39
	s_nop 1
	v_cndmask_b32_e32 v40, 0, v40, vcc
	v_cmp_ngt_f32_e32 vcc, s56, v39
	s_nop 1
	v_cndmask_b32_e32 v39, 1.0, v40, vcc
	v_cmp_ngt_f32_e32 vcc, s56, v38
	s_nop 1
	v_cndmask_b32_e32 v38, 1.0, v27, vcc
	v_pk_mul_f32 v[30:31], v[30:31], v[38:39]
	v_mul_f32_e32 v27, 0x3fb8aa3b, v37
	v_pk_mul_f32 v[30:31], v[30:31], v[34:35]
	v_add_u32_e32 v34, s7, v50
	v_cvt_pk_bf16_f32 v33, v30, v31
	global_store_dwordx2 v[48:49], v[32:33], off offset:1120
	v_lshl_add_u64 v[32:33], s[26:27], 0, v[144:145]
	v_lshl_add_u64 v[48:49], v[32:33], 0, v[68:69]
	global_load_dwordx4 v[118:121], v[48:49], off
	global_load_dwordx4 v[122:125], v[48:49], off offset:64
	v_lshl_add_u64 v[32:33], s[24:25], 0, v[144:145]
	v_lshl_add_u32 v87, v34, 1, s0
	v_lshl_add_u64 v[50:51], v[32:33], 0, v[68:69]
	global_load_dwordx4 v[126:129], v[50:51], off
	global_load_dwordx4 v[130:133], v[50:51], off offset:64
	ds_read_b128 v[32:35], v87
	s_waitcnt vmcnt(3) lgkmcnt(0)
	v_mfma_f32_16x16x32_bf16 v[36:39], v[118:121], v[32:35], 0
	ds_read_b128 v[44:47], v87 offset:64
	s_ashr_i32 s7, s5, 31
	v_mov_b32_e32 v55, s7
	s_waitcnt vmcnt(1)
	v_mfma_f32_16x16x32_bf16 v[32:35], v[126:129], v[32:35], 0
	s_nop 0
	ds_read_b64 v[56:57], v56
	s_or_b32 s7, s5, 0x50
	s_waitcnt vmcnt(1) lgkmcnt(1)
	v_mfma_f32_16x16x32_bf16 v[40:43], v[122:125], v[44:47], v[36:39]
	s_nop 2
	v_lshlrev_b64 v[36:37], 2, v[54:55]
	v_lshl_add_u64 v[84:85], s[30:31], 0, v[36:37]
	v_lshl_add_u64 v[72:73], s[28:29], 0, v[36:37]
	s_waitcnt vmcnt(0)
	v_mfma_f32_16x16x32_bf16 v[32:35], v[130:133], v[44:47], v[32:35]
	global_load_dwordx4 v[44:47], v[84:85], off offset:256
	global_load_dwordx4 v[48:51], v[72:73], off offset:256
	v_lshl_add_u64 v[82:83], s[16:17], 0, v[36:37]
	global_load_dwordx4 v[36:39], v[82:83], off offset:256
	s_ashr_i32 s24, s7, 6
	s_ashr_i32 s25, s24, 31
	s_lshl_b64 s[24:25], s[24:25], 13
	s_add_u32 s26, s57, s24
	v_lshl_add_u64 v[80:81], v[54:55], 1, v[52:53]
	s_addc_u32 s27, s58, s25
	s_add_u32 s24, s59, s24
	s_addc_u32 s25, s60, s25
	v_exp_f32_e32 v27, v27
	s_waitcnt vmcnt(2)
	v_add_f32_e32 v32, v32, v44
	v_mul_f32_e32 v32, 0xbfb8aa3b, v32
	v_exp_f32_e32 v32, v32
	s_waitcnt vmcnt(1)
	v_add_f32_e32 v40, v40, v48
	v_mul_f32_e32 v40, 0xbfb8aa3b, v40
	v_exp_f32_e32 v40, v40
	v_add_f32_e32 v32, 1.0, v32
	v_rcp_f32_e32 v44, v32
	v_add_f32_e32 v32, v41, v49
	v_mul_f32_e32 v32, 0xbfb8aa3b, v32
	v_exp_f32_e32 v32, v32
	v_add_f32_e32 v40, 1.0, v40
	v_rcp_f32_e32 v40, v40
	s_waitcnt lgkmcnt(0)
	v_lshlrev_b32_e32 v48, 16, v56
	v_add_f32_e32 v32, 1.0, v32
	v_rcp_f32_e32 v41, v32
	v_add_f32_e32 v32, v33, v45
	v_and_b32_e32 v49, 0xffff0000, v56
	v_mul_f32_e32 v32, 0xbfb8aa3b, v32
	s_waitcnt vmcnt(0)
; #define LAS __attribute__((address_space(3)))
; __device__ __forceinline__ unsigned pk2(float lo, float hi) { return pg8::cvt_pk_bf16(lo, hi); }
; __device__ __forceinline__ float sigmoidf_(float x) { return __builtin_amdgcn_rcpf(1.0f + __expf(-x)); }
; template <bool FULL> __device__ __forceinline__ void lru_tile(const Args& a, int l, int tile, LAS unsigned char* lds, int tid, int lane, int wave) {
;     ...
;         for (int et = 0; et < 8; ++et) {
;             const int e0 = chh * 128 + et * 16, nb = e0 >> 6, el = e0 & 63;
;             f32x4 ra = {0.f, 0.f, 0.f, 0.f}, ia = {0.f, 0.f, 0.f, 0.f};
; #pragma unroll
;             for (int ks = 0; ks < 2; ++ks) {
;                 const bf16x8 xv = *(const LAS bf16x8*)(lds + OFF_XC + ((cb * 16 + fr) * 264 + nb * 64 + 32 * ks + 8 * fq) * 2);
;                 const bf16x8 wa = *(const bf16x8*)(WA + (size_t)nb * 4096 + (el + fr) * 64 + 32 * ks + 8 * fq);
;                 const bf16x8 wx = *(const bf16x8*)(WX + (size_t)nb * 4096 + (el + fr) * 64 + 32 * ks + 8 * fq);
;                 MFMA16(wa, xv, ra); MFMA16(wx, xv, ia);
;             }
;             const int c0 = e0 + 4 * fq;
;             const f32x4 ba = *(const f32x4*)(a.in[22] + (size_t)l * 256 + c0), bx = *(const f32x4*)(a.in[24] + (size_t)l * 256 + c0), c8v = *(const f32x4*)(c8t + c0);
;             const u32x2 xr = *(const LAS u32x2*)(lds + OFF_XC + ((cb * 16 + fr) * 264 + c0) * 2);
;             float lav[4];
;             const float xcv[4] = {__uint_as_float(xr.x << 16), __uint_as_float(xr.x & 0xffff0000u), __uint_as_float(xr.y << 16), __uint_as_float(xr.y & 0xffff0000u)};
; #pragma unroll
;             for (int r = 0; r < 4; ++r) {
;                 const float rg = sigmoidf_(ra[r] + ba[r]), ig = sigmoidf_(ia[r] + bx[r]);
;                 const float la = c8v[r] * rg; const float av_ = __expf(la); const float m2 = -expm1f(2.0f * la);
;                 av[et][r] = av_; bv[et][r] = sqrtf(fmaxf(m2, 0.f)) * ig * xcv[r]; lav[r] = la;
;             }
;             {
;               bf16* yr = Y + (size_t)(t0 + cb * 16 + fr) * DM + c0;
;               u32x2 wl_; wl_.x = pk2(lav[0], lav[1]); wl_.y = pk2(lav[2], lav[3]); *(u32x2*)(yr + 768) = wl_;
;               u32x2 wb_; wb_.x = pk2(bv[et][0], bv[et][1]); wb_.y = pk2(bv[et][2], bv[et][3]); *(u32x2*)(yr + 512) = wb_; }
	v_pk_mul_f32 v[40:41], v[36:37], v[40:41]
	v_exp_f32_e32 v32, v32
	v_pk_add_f32 v[36:37], v[40:41], v[40:41]
	v_add_f32_e32 v42, v42, v50
	v_mul_f32_e32 v33, 0x3fb8aa3b, v36
	v_rndne_f32_e32 v33, v33
	v_fmamk_f32 v56, v33, 0xbf317218, v36
	v_fmac_f32_e32 v56, 0x3102e308, v33
	v_fmamk_f32 v58, v56, 0x395133b1, v177
	v_cmp_eq_f32_e32 vcc, s2, v33
	v_cvt_i32_f32_e32 v33, v33
	v_fmaak_f32 v58, v56, v58, 0x3c0887f9
	v_fmaak_f32 v58, v56, v58, 0x3d2aaa81
	v_fmaak_f32 v58, v56, v58, 0x3e2aaaab
	v_fma_f32 v58, v56, v58, 0.5
	v_ldexp_f32 v33, 1.0, v33
	v_mul_f32_e32 v58, v56, v58
	v_cndmask_b32_e32 v33, v33, v195, vcc
	v_fmac_f32_e32 v56, v56, v58
	v_add_f32_e32 v58, -1.0, v33
	v_fmac_f32_e32 v58, v33, v56
	v_add_f32_e32 v33, v58, v58
	v_cndmask_b32_e32 v33, v58, v33, vcc
	v_max_f32_e64 v33, -v33, 0
	v_cmp_gt_f32_e32 vcc, s19, v33
	v_mul_f32_e32 v56, 0x4f800000, v33
	v_add_f32_e32 v34, v34, v46
	v_cndmask_b32_e32 v33, v33, v56, vcc
	v_sqrt_f32_e32 v56, v33
	v_mul_f32_e32 v42, 0xbfb8aa3b, v42
	v_mul_f32_e32 v34, 0xbfb8aa3b, v34
	v_add_f32_e32 v32, 1.0, v32
	v_add_u32_e32 v58, -1, v56
	v_fma_f32 v59, -v58, v56, v33
	v_cmp_ge_f32_e64 s[36:37], 0, v59
	v_add_u32_e32 v59, 1, v56
	v_exp_f32_e32 v42, v42
	v_cndmask_b32_e64 v58, v56, v58, s[36:37]
	v_fma_f32 v56, -v59, v56, v33
	v_cmp_lt_f32_e64 s[36:37], 0, v56
	v_exp_f32_e32 v34, v34
	v_rcp_f32_e32 v45, v32
	v_cndmask_b32_e64 v56, v58, v59, s[36:37]
	v_mul_f32_e32 v58, 0x37800000, v56
	v_cndmask_b32_e32 v56, v56, v58, vcc
	v_cmp_class_f32_e32 vcc, v33, v178
	v_add_f32_e32 v42, 1.0, v42
	v_add_f32_e32 v34, 1.0, v34
	v_cndmask_b32_e32 v33, v56, v33, vcc
	v_mul_f32_e32 v56, 0x3fb8aa3b, v37
	v_rndne_f32_e32 v56, v56
	v_fmamk_f32 v58, v56, 0xbf317218, v37
	v_fmac_f32_e32 v58, 0x3102e308, v56
	v_fmamk_f32 v59, v58, 0x395133b1, v177
	v_cmp_eq_f32_e32 vcc, s2, v56
	v_cvt_i32_f32_e32 v56, v56
	v_fmaak_f32 v59, v58, v59, 0x3c0887f9
	v_fmaak_f32 v59, v58, v59, 0x3d2aaa81
	v_fmaak_f32 v59, v58, v59, 0x3e2aaaab
	v_fma_f32 v59, v58, v59, 0.5
	v_ldexp_f32 v56, 1.0, v56
	v_mul_f32_e32 v59, v58, v59
	v_cndmask_b32_e32 v56, v56, v195, vcc
	v_fmac_f32_e32 v58, v58, v59
	v_add_f32_e32 v59, -1.0, v56
	v_fmac_f32_e32 v59, v56, v58
	v_add_f32_e32 v56, v59, v59
	v_cndmask_b32_e32 v56, v59, v56, vcc
	v_max_f32_e64 v56, -v56, 0
	v_cmp_gt_f32_e32 vcc, s19, v56
	v_mul_f32_e32 v58, 0x4f800000, v56
	v_mul_f32_e32 v32, 0x3fb8aa3b, v40
	v_cndmask_b32_e32 v56, v56, v58, vcc
	v_sqrt_f32_e32 v58, v56
	v_lshlrev_b32_e32 v46, 16, v57
	v_cvt_pk_bf16_f32 v40, v40, v41
	v_exp_f32_e32 v32, v32
	v_add_u32_e32 v59, -1, v58
	v_fma_f32 v62, -v59, v58, v56
	v_cmp_ge_f32_e64 s[36:37], 0, v62
	v_add_u32_e32 v62, 1, v58
	s_nop 0
	v_cndmask_b32_e64 v59, v58, v59, s[36:37]
	v_fma_f32 v58, -v62, v58, v56
	v_cmp_lt_f32_e64 s[36:37], 0, v58
	s_nop 1
	v_cndmask_b32_e64 v58, v59, v62, s[36:37]
	v_mul_f32_e32 v59, 0x37800000, v58
	v_cndmask_b32_e32 v58, v58, v59, vcc
	v_cmp_class_f32_e32 vcc, v56, v178
	v_or_b32_e32 v62, s7, v86
	v_mad_u32_u24 v62, v79, s12, v62
	v_cndmask_b32_e32 v56, v58, v56, vcc
	v_cmp_nlt_f32_e32 vcc, s86, v36
	v_lshl_add_u32 v62, v62, 1, s0
	s_or_b32 s7, s5, 0x60
	v_cndmask_b32_e32 v33, 0, v33, vcc
	v_cmp_nlt_f32_e32 vcc, s86, v37
	v_or_b32_e32 v74, s7, v86
	v_mad_u32_u24 v74, v79, s12, v74
	v_cndmask_b32_e32 v56, 0, v56, vcc
	v_cmp_ngt_f32_e32 vcc, s56, v37
	v_lshl_add_u32 v74, v74, 1, s0
	s_nop 0
	v_cndmask_b32_e32 v37, 1.0, v56, vcc
	v_cmp_ngt_f32_e32 vcc, s56, v36
	s_nop 1
	v_cndmask_b32_e32 v36, 1.0, v33, vcc
	v_pk_mul_f32 v[36:37], v[44:45], v[36:37]
	v_rcp_f32_e32 v44, v42
	v_rcp_f32_e32 v42, v34
	v_add_f32_e32 v34, v43, v51
	v_mul_f32_e32 v34, 0xbfb8aa3b, v34
	v_exp_f32_e32 v34, v34
	v_pk_mul_f32 v[36:37], v[36:37], v[48:49]
	v_mul_f32_e32 v33, 0x3fb8aa3b, v41
	v_exp_f32_e32 v33, v33
	v_add_f32_e32 v34, 1.0, v34
	v_rcp_f32_e32 v45, v34
	v_add_f32_e32 v34, v35, v47
	v_mul_f32_e32 v34, 0xbfb8aa3b, v34
	v_exp_f32_e32 v34, v34
	v_pk_mul_f32 v[44:45], v[38:39], v[44:45]
	v_and_b32_e32 v47, 0xffff0000, v57
	v_pk_add_f32 v[38:39], v[44:45], v[44:45]
	v_add_f32_e32 v34, 1.0, v34
	v_mul_f32_e32 v35, 0x3fb8aa3b, v38
	v_rndne_f32_e32 v35, v35
	v_fmamk_f32 v48, v35, 0xbf317218, v38
	v_fmac_f32_e32 v48, 0x3102e308, v35
	v_fmamk_f32 v49, v48, 0x395133b1, v177
	v_cmp_eq_f32_e32 vcc, s2, v35
	v_cvt_i32_f32_e32 v35, v35
	v_fmaak_f32 v49, v48, v49, 0x3c0887f9
	v_fmaak_f32 v49, v48, v49, 0x3d2aaa81
	v_fmaak_f32 v49, v48, v49, 0x3e2aaaab
	v_fma_f32 v49, v48, v49, 0.5
	v_ldexp_f32 v35, 1.0, v35
	v_mul_f32_e32 v49, v48, v49
	v_cndmask_b32_e32 v35, v35, v195, vcc
	v_fmac_f32_e32 v48, v48, v49
	v_add_f32_e32 v49, -1.0, v35
	v_fmac_f32_e32 v49, v35, v48
	v_add_f32_e32 v35, v49, v49
	v_cndmask_b32_e32 v35, v49, v35, vcc
	v_max_f32_e64 v35, -v35, 0
	v_cmp_gt_f32_e32 vcc, s19, v35
	v_mul_f32_e32 v48, 0x4f800000, v35
	v_rcp_f32_e32 v43, v34
	v_cndmask_b32_e32 v35, v35, v48, vcc
	v_sqrt_f32_e32 v48, v35
	v_cvt_pk_bf16_f32 v41, v44, v45
	global_store_dwordx2 v[80:81], v[40:41], off offset:1664
	v_cvt_pk_bf16_f32 v40, v36, v37
	v_add_u32_e32 v49, -1, v48
	v_fma_f32 v50, -v49, v48, v35
	v_cmp_ge_f32_e64 s[36:37], 0, v50
	v_add_u32_e32 v50, 1, v48
	v_mul_f32_e32 v34, 0x3fb8aa3b, v44
	v_cndmask_b32_e64 v49, v48, v49, s[36:37]
	v_fma_f32 v48, -v50, v48, v35
	v_cmp_lt_f32_e64 s[36:37], 0, v48
	v_exp_f32_e32 v34, v34
	s_nop 0
	v_cndmask_b32_e64 v48, v49, v50, s[36:37]
	v_mul_f32_e32 v49, 0x37800000, v48
	v_cndmask_b32_e32 v48, v48, v49, vcc
	v_cmp_class_f32_e32 vcc, v35, v178
	s_nop 1
	v_cndmask_b32_e32 v35, v48, v35, vcc
	v_mul_f32_e32 v48, 0x3fb8aa3b, v39
	v_rndne_f32_e32 v48, v48
	v_fmamk_f32 v49, v48, 0xbf317218, v39
	v_fmac_f32_e32 v49, 0x3102e308, v48
; #define LAS __attribute__((address_space(3)))
; __device__ __forceinline__ unsigned pk2(float lo, float hi) { return pg8::cvt_pk_bf16(lo, hi); }
; __device__ __forceinline__ float sigmoidf_(float x) { return __builtin_amdgcn_rcpf(1.0f + __expf(-x)); }
; template <bool FULL> __device__ __forceinline__ void lru_tile(const Args& a, int l, int tile, LAS unsigned char* lds, int tid, int lane, int wave) {
;     ...
;         for (int et = 0; et < 8; ++et) {
;             const int e0 = chh * 128 + et * 16, nb = e0 >> 6, el = e0 & 63;
;             f32x4 ra = {0.f, 0.f, 0.f, 0.f}, ia = {0.f, 0.f, 0.f, 0.f};
; #pragma unroll
;             for (int ks = 0; ks < 2; ++ks) {
;                 const bf16x8 xv = *(const LAS bf16x8*)(lds + OFF_XC + ((cb * 16 + fr) * 264 + nb * 64 + 32 * ks + 8 * fq) * 2);
;                 const bf16x8 wa = *(const bf16x8*)(WA + (size_t)nb * 4096 + (el + fr) * 64 + 32 * ks + 8 * fq);
;                 const bf16x8 wx = *(const bf16x8*)(WX + (size_t)nb * 4096 + (el + fr) * 64 + 32 * ks + 8 * fq);
;                 MFMA16(wa, xv, ra); MFMA16(wx, xv, ia);
;             }
;             const int c0 = e0 + 4 * fq;
;             const f32x4 ba = *(const f32x4*)(a.in[22] + (size_t)l * 256 + c0), bx = *(const f32x4*)(a.in[24] + (size_t)l * 256 + c0), c8v = *(const f32x4*)(c8t + c0);
;             const u32x2 xr = *(const LAS u32x2*)(lds + OFF_XC + ((cb * 16 + fr) * 264 + c0) * 2);
;             float lav[4];
;             const float xcv[4] = {__uint_as_float(xr.x << 16), __uint_as_float(xr.x & 0xffff0000u), __uint_as_float(xr.y << 16), __uint_as_float(xr.y & 0xffff0000u)};
; #pragma unroll
;             for (int r = 0; r < 4; ++r) {
;                 const float rg = sigmoidf_(ra[r] + ba[r]), ig = sigmoidf_(ia[r] + bx[r]);
;                 const float la = c8v[r] * rg; const float av_ = __expf(la); const float m2 = -expm1f(2.0f * la);
;                 av[et][r] = av_; bv[et][r] = sqrtf(fmaxf(m2, 0.f)) * ig * xcv[r]; lav[r] = la;
;             }
;             {
;               bf16* yr = Y + (size_t)(t0 + cb * 16 + fr) * DM + c0;
;               u32x2 wl_; wl_.x = pk2(lav[0], lav[1]); wl_.y = pk2(lav[2], lav[3]); *(u32x2*)(yr + 768) = wl_;
;               u32x2 wb_; wb_.x = pk2(bv[et][0], bv[et][1]); wb_.y = pk2(bv[et][2], bv[et][3]); *(u32x2*)(yr + 512) = wb_; }
	v_fmamk_f32 v50, v49, 0x395133b1, v177
	v_cmp_eq_f32_e32 vcc, s2, v48
	v_cvt_i32_f32_e32 v48, v48
	v_fmaak_f32 v50, v49, v50, 0x3c0887f9
	v_fmaak_f32 v50, v49, v50, 0x3d2aaa81
	v_fmaak_f32 v50, v49, v50, 0x3e2aaaab
	v_fma_f32 v50, v49, v50, 0.5
	v_ldexp_f32 v48, 1.0, v48
	v_mul_f32_e32 v50, v49, v50
	v_cndmask_b32_e32 v48, v48, v195, vcc
	v_fmac_f32_e32 v49, v49, v50
	v_add_f32_e32 v50, -1.0, v48
	v_fmac_f32_e32 v50, v48, v49
	v_add_f32_e32 v48, v50, v50
	v_cndmask_b32_e32 v48, v50, v48, vcc
	v_max_f32_e64 v48, -v48, 0
	v_cmp_gt_f32_e32 vcc, s19, v48
	v_mul_f32_e32 v49, 0x4f800000, v48
	s_nop 0
	v_cndmask_b32_e32 v48, v48, v49, vcc
	v_sqrt_f32_e32 v49, v48
	s_nop 0
	v_add_u32_e32 v50, -1, v49
	v_fma_f32 v51, -v50, v49, v48
	v_cmp_ge_f32_e64 s[36:37], 0, v51
	v_add_u32_e32 v51, 1, v49
	s_nop 0
	v_cndmask_b32_e64 v50, v49, v50, s[36:37]
	v_fma_f32 v49, -v51, v49, v48
	v_cmp_lt_f32_e64 s[36:37], 0, v49
	s_nop 1
	v_cndmask_b32_e64 v49, v50, v51, s[36:37]
	v_mul_f32_e32 v50, 0x37800000, v49
	v_cndmask_b32_e32 v49, v49, v50, vcc
	v_cmp_class_f32_e32 vcc, v48, v178
	s_nop 1
	v_cndmask_b32_e32 v48, v49, v48, vcc
	v_cmp_nlt_f32_e32 vcc, s86, v38
	s_nop 1
	v_cndmask_b32_e32 v35, 0, v35, vcc
	v_cmp_nlt_f32_e32 vcc, s86, v39
	s_nop 1
	v_cndmask_b32_e32 v48, 0, v48, vcc
	v_cmp_ngt_f32_e32 vcc, s56, v39
	s_nop 1
	v_cndmask_b32_e32 v39, 1.0, v48, vcc
	v_cmp_ngt_f32_e32 vcc, s56, v38
	s_nop 1
	v_cndmask_b32_e32 v38, 1.0, v35, vcc
	v_pk_mul_f32 v[38:39], v[42:43], v[38:39]
	v_mul_f32_e32 v35, 0x3fb8aa3b, v45
	v_pk_mul_f32 v[38:39], v[38:39], v[46:47]
	v_exp_f32_e32 v35, v35
	v_cvt_pk_bf16_f32 v41, v38, v39
	global_store_dwordx2 v[80:81], v[40:41], off offset:1152
	v_lshl_add_u64 v[40:41], s[26:27], 0, v[144:145]
	v_lshl_add_u64 v[52:53], v[40:41], 0, v[68:69]
	global_load_dwordx4 v[118:121], v[52:53], off offset:2048
	global_load_dwordx4 v[122:125], v[52:53], off offset:2112
	v_lshl_add_u64 v[40:41], s[24:25], 0, v[144:145]
	v_lshl_add_u64 v[56:57], v[40:41], 0, v[68:69]
	global_load_dwordx4 v[126:129], v[56:57], off offset:2048
	global_load_dwordx4 v[130:133], v[56:57], off offset:2112
	ds_read_b128 v[40:43], v87
	s_waitcnt vmcnt(3) lgkmcnt(0)
	v_mfma_f32_16x16x32_bf16 v[44:47], v[118:121], v[40:43], 0
	s_ashr_i32 s24, s7, 6
	s_ashr_i32 s25, s24, 31
	s_lshl_b64 s[24:25], s[24:25], 13
	s_waitcnt vmcnt(1)
	v_mfma_f32_16x16x32_bf16 v[40:43], v[126:129], v[40:43], 0
	ds_read_b128 v[48:51], v87 offset:64
	s_nop 0
	s_add_u32 s26, s57, s24
	s_waitcnt vmcnt(1) lgkmcnt(0)
	v_mfma_f32_16x16x32_bf16 v[52:55], v[122:125], v[48:51], v[44:47]
	s_addc_u32 s27, s58, s25
	s_add_u32 s24, s59, s24
	s_addc_u32 s25, s60, s25
	s_waitcnt vmcnt(0)
	v_mfma_f32_16x16x32_bf16 v[44:47], v[130:133], v[48:51], v[40:43]
	global_load_dwordx4 v[56:59], v[72:73], off offset:320
	global_load_dwordx4 v[48:51], v[84:85], off offset:320
	s_nop 0
	global_load_dwordx4 v[40:43], v[82:83], off offset:320
	ds_read_b64 v[62:63], v62
	s_or_b32 s5, s5, 0x70
	v_or_b32_e32 v86, s5, v86
	v_mad_u32_u24 v79, v79, s12, v86
	v_lshl_add_u32 v79, v79, 1, s0
	s_waitcnt vmcnt(2)
	v_add_f32_e32 v52, v52, v56
	s_waitcnt vmcnt(1)
	v_add_f32_e32 v44, v44, v48
	v_add_f32_e32 v48, v53, v57
	v_mul_f32_e32 v52, 0xbfb8aa3b, v52
	v_mul_f32_e32 v48, 0xbfb8aa3b, v48
	v_exp_f32_e32 v52, v52
	v_exp_f32_e32 v48, v48
	v_add_f32_e32 v45, v45, v49
	s_waitcnt lgkmcnt(0)
	v_lshlrev_b32_e32 v56, 16, v62
	v_add_f32_e32 v52, 1.0, v52
	v_add_f32_e32 v48, 1.0, v48
	v_rcp_f32_e32 v52, v52
	v_rcp_f32_e32 v53, v48
	v_and_b32_e32 v57, 0xffff0000, v62
	v_mul_f32_e32 v44, 0xbfb8aa3b, v44
	v_mul_f32_e32 v45, 0xbfb8aa3b, v45
	s_waitcnt vmcnt(0)
	v_pk_mul_f32 v[48:49], v[40:41], v[52:53]
	v_exp_f32_e32 v44, v44
	v_pk_add_f32 v[52:53], v[48:49], v[48:49]
	v_exp_f32_e32 v45, v45
	v_mul_f32_e32 v41, 0x3fb8aa3b, v52
	v_rndne_f32_e32 v41, v41
	v_fmamk_f32 v62, v41, 0xbf317218, v52
	v_fmac_f32_e32 v62, 0x3102e308, v41
	v_fmamk_f32 v64, v62, 0x395133b1, v177
	v_cmp_eq_f32_e32 vcc, s2, v41
	v_cvt_i32_f32_e32 v41, v41
	v_fmaak_f32 v64, v62, v64, 0x3c0887f9
	v_fmaak_f32 v64, v62, v64, 0x3d2aaa81
	v_fmaak_f32 v64, v62, v64, 0x3e2aaaab
	v_fma_f32 v64, v62, v64, 0.5
	v_ldexp_f32 v41, 1.0, v41
	v_mul_f32_e32 v64, v62, v64
	v_cndmask_b32_e32 v41, v41, v195, vcc
	v_fmac_f32_e32 v62, v62, v64
	v_add_f32_e32 v64, -1.0, v41
	v_fmac_f32_e32 v64, v41, v62
	v_add_f32_e32 v41, v64, v64
	v_cndmask_b32_e32 v41, v64, v41, vcc
	v_max_f32_e64 v41, -v41, 0
	v_cmp_gt_f32_e32 vcc, s19, v41
	v_mul_f32_e32 v62, 0x4f800000, v41
	v_add_f32_e32 v44, 1.0, v44
	v_cndmask_b32_e32 v41, v41, v62, vcc
	v_sqrt_f32_e32 v62, v41
	v_add_f32_e32 v45, 1.0, v45
	v_rcp_f32_e32 v44, v44
	v_rcp_f32_e32 v45, v45
	v_add_u32_e32 v64, -1, v62
	v_fma_f32 v65, -v64, v62, v41
	v_cmp_ge_f32_e64 s[36:37], 0, v65
	v_add_u32_e32 v65, 1, v62
	v_add_f32_e32 v46, v46, v50
	v_cndmask_b32_e64 v64, v62, v64, s[36:37]
	v_fma_f32 v62, -v65, v62, v41
	v_cmp_lt_f32_e64 s[36:37], 0, v62
	v_add_f32_e32 v50, v55, v59
	v_mul_f32_e32 v50, 0xbfb8aa3b, v50
	v_cndmask_b32_e64 v62, v64, v65, s[36:37]
	v_mul_f32_e32 v64, 0x37800000, v62
	v_cndmask_b32_e32 v62, v62, v64, vcc
	v_cmp_class_f32_e32 vcc, v41, v178
	v_exp_f32_e32 v50, v50
	v_add_f32_e32 v47, v47, v51
	v_cndmask_b32_e32 v41, v62, v41, vcc
	v_mul_f32_e32 v62, 0x3fb8aa3b, v53
	v_rndne_f32_e32 v62, v62
	v_fmamk_f32 v64, v62, 0xbf317218, v53
	v_fmac_f32_e32 v64, 0x3102e308, v62
	v_fmamk_f32 v65, v64, 0x395133b1, v177
	v_cmp_eq_f32_e32 vcc, s2, v62
	v_cvt_i32_f32_e32 v62, v62
	v_fmaak_f32 v65, v64, v65, 0x3c0887f9
	v_fmaak_f32 v65, v64, v65, 0x3d2aaa81
	v_fmaak_f32 v65, v64, v65, 0x3e2aaaab
	v_fma_f32 v65, v64, v65, 0.5
	v_ldexp_f32 v62, 1.0, v62
	v_mul_f32_e32 v65, v64, v65
; #define LAS __attribute__((address_space(3)))
; __device__ __forceinline__ unsigned pk2(float lo, float hi) { return pg8::cvt_pk_bf16(lo, hi); }
; __device__ __forceinline__ float sigmoidf_(float x) { return __builtin_amdgcn_rcpf(1.0f + __expf(-x)); }
; template <bool FULL> __device__ __forceinline__ void lru_tile(const Args& a, int l, int tile, LAS unsigned char* lds, int tid, int lane, int wave) {
;     ...
;         for (int et = 0; et < 8; ++et) {
;             const int e0 = chh * 128 + et * 16, nb = e0 >> 6, el = e0 & 63;
;             f32x4 ra = {0.f, 0.f, 0.f, 0.f}, ia = {0.f, 0.f, 0.f, 0.f};
; #pragma unroll
;             for (int ks = 0; ks < 2; ++ks) {
;                 const bf16x8 xv = *(const LAS bf16x8*)(lds + OFF_XC + ((cb * 16 + fr) * 264 + nb * 64 + 32 * ks + 8 * fq) * 2);
;                 const bf16x8 wa = *(const bf16x8*)(WA + (size_t)nb * 4096 + (el + fr) * 64 + 32 * ks + 8 * fq);
;                 const bf16x8 wx = *(const bf16x8*)(WX + (size_t)nb * 4096 + (el + fr) * 64 + 32 * ks + 8 * fq);
;                 MFMA16(wa, xv, ra); MFMA16(wx, xv, ia);
;             }
;             const int c0 = e0 + 4 * fq;
;             const f32x4 ba = *(const f32x4*)(a.in[22] + (size_t)l * 256 + c0), bx = *(const f32x4*)(a.in[24] + (size_t)l * 256 + c0), c8v = *(const f32x4*)(c8t + c0);
;             const u32x2 xr = *(const LAS u32x2*)(lds + OFF_XC + ((cb * 16 + fr) * 264 + c0) * 2);
;             float lav[4];
;             const float xcv[4] = {__uint_as_float(xr.x << 16), __uint_as_float(xr.x & 0xffff0000u), __uint_as_float(xr.y << 16), __uint_as_float(xr.y & 0xffff0000u)};
; #pragma unroll
;             for (int r = 0; r < 4; ++r) {
;                 const float rg = sigmoidf_(ra[r] + ba[r]), ig = sigmoidf_(ia[r] + bx[r]);
;                 const float la = c8v[r] * rg; const float av_ = __expf(la); const float m2 = -expm1f(2.0f * la);
;                 av[et][r] = av_; bv[et][r] = sqrtf(fmaxf(m2, 0.f)) * ig * xcv[r]; lav[r] = la;
;             }
;             {
;               bf16* yr = Y + (size_t)(t0 + cb * 16 + fr) * DM + c0;
;               u32x2 wl_; wl_.x = pk2(lav[0], lav[1]); wl_.y = pk2(lav[2], lav[3]); *(u32x2*)(yr + 768) = wl_;
;               u32x2 wb_; wb_.x = pk2(bv[et][0], bv[et][1]); wb_.y = pk2(bv[et][2], bv[et][3]); *(u32x2*)(yr + 512) = wb_; }
	v_cndmask_b32_e32 v62, v62, v195, vcc
	v_fmac_f32_e32 v64, v64, v65
	v_add_f32_e32 v65, -1.0, v62
	v_fmac_f32_e32 v65, v62, v64
	v_add_f32_e32 v62, v65, v65
	v_cndmask_b32_e32 v62, v65, v62, vcc
	v_max_f32_e64 v62, -v62, 0
	v_cmp_gt_f32_e32 vcc, s19, v62
	v_mul_f32_e32 v64, 0x4f800000, v62
	v_add_f32_e32 v50, 1.0, v50
	v_cndmask_b32_e32 v62, v62, v64, vcc
	v_sqrt_f32_e32 v64, v62
	v_mul_f32_e32 v46, 0xbfb8aa3b, v46
	v_mul_f32_e32 v47, 0xbfb8aa3b, v47
	v_exp_f32_e32 v46, v46
	v_add_u32_e32 v65, -1, v64
	v_fma_f32 v66, -v65, v64, v62
	v_cmp_ge_f32_e64 s[36:37], 0, v66
	v_add_u32_e32 v66, 1, v64
	v_exp_f32_e32 v47, v47
	v_cndmask_b32_e64 v65, v64, v65, s[36:37]
	v_fma_f32 v64, -v66, v64, v62
	v_cmp_lt_f32_e64 s[36:37], 0, v64
	v_add_f32_e32 v46, 1.0, v46
	v_add_f32_e32 v47, 1.0, v47
	v_cndmask_b32_e64 v64, v65, v66, s[36:37]
	v_mul_f32_e32 v65, 0x37800000, v64
	v_cndmask_b32_e32 v64, v64, v65, vcc
	v_cmp_class_f32_e32 vcc, v62, v178
	v_rcp_f32_e32 v46, v46
	v_rcp_f32_e32 v47, v47
	v_cndmask_b32_e32 v62, v64, v62, vcc
	v_cmp_nlt_f32_e32 vcc, s86, v52
	v_mul_f32_e32 v40, 0x3fb8aa3b, v48
	v_and_b32_e32 v51, 0xffff0000, v63
	v_cndmask_b32_e32 v41, 0, v41, vcc
	v_cmp_nlt_f32_e32 vcc, s86, v53
	v_cvt_pk_bf16_f32 v48, v48, v49
	v_exp_f32_e32 v40, v40
	s_nop 0
	v_cndmask_b32_e32 v62, 0, v62, vcc
	v_cmp_ngt_f32_e32 vcc, s56, v53
	s_nop 1
	v_cndmask_b32_e32 v53, 1.0, v62, vcc
	v_cmp_ngt_f32_e32 vcc, s56, v52
	s_nop 1
	v_cndmask_b32_e32 v52, 1.0, v41, vcc
	v_pk_mul_f32 v[44:45], v[44:45], v[52:53]
	v_add_f32_e32 v52, v54, v58
	v_mul_f32_e32 v52, 0xbfb8aa3b, v52
	v_exp_f32_e32 v52, v52
	v_rcp_f32_e32 v53, v50
	v_pk_mul_f32 v[44:45], v[44:45], v[56:57]
	v_mul_f32_e32 v41, 0x3fb8aa3b, v49
	v_add_f32_e32 v52, 1.0, v52
	v_rcp_f32_e32 v52, v52
	v_lshlrev_b32_e32 v50, 16, v63
	v_exp_f32_e32 v41, v41
	v_pk_mul_f32 v[52:53], v[42:43], v[52:53]
	s_nop 0
	v_pk_add_f32 v[54:55], v[52:53], v[52:53]
	v_cvt_pk_bf16_f32 v49, v52, v53
	global_store_dwordx2 v[80:81], v[48:49], off offset:1696
	v_mul_f32_e32 v43, 0x3fb8aa3b, v54
	v_rndne_f32_e32 v43, v43
	v_fmamk_f32 v56, v43, 0xbf317218, v54
	v_fmac_f32_e32 v56, 0x3102e308, v43
	v_fmamk_f32 v57, v56, 0x395133b1, v177
	v_cmp_eq_f32_e32 vcc, s2, v43
	v_cvt_i32_f32_e32 v43, v43
	v_fmaak_f32 v57, v56, v57, 0x3c0887f9
	v_fmaak_f32 v57, v56, v57, 0x3d2aaa81
	v_fmaak_f32 v57, v56, v57, 0x3e2aaaab
	v_fma_f32 v57, v56, v57, 0.5
	v_ldexp_f32 v43, 1.0, v43
	v_mul_f32_e32 v57, v56, v57
	v_cndmask_b32_e32 v43, v43, v195, vcc
	v_fmac_f32_e32 v56, v56, v57
	v_add_f32_e32 v57, -1.0, v43
	v_fmac_f32_e32 v57, v43, v56
	v_add_f32_e32 v43, v57, v57
	v_cndmask_b32_e32 v43, v57, v43, vcc
	v_max_f32_e64 v43, -v43, 0
	v_cmp_gt_f32_e32 vcc, s19, v43
	v_mul_f32_e32 v56, 0x4f800000, v43
	v_cvt_pk_bf16_f32 v48, v44, v45
	v_mul_f32_e32 v42, 0x3fb8aa3b, v52
	v_cndmask_b32_e32 v43, v43, v56, vcc
	v_sqrt_f32_e32 v56, v43
	v_exp_f32_e32 v42, v42
	v_add_u32_e32 v57, -1, v56
	v_fma_f32 v58, -v57, v56, v43
	v_cmp_ge_f32_e64 s[36:37], 0, v58
	v_add_u32_e32 v58, 1, v56
	s_nop 0
	v_cndmask_b32_e64 v57, v56, v57, s[36:37]
	v_fma_f32 v56, -v58, v56, v43
	v_cmp_lt_f32_e64 s[36:37], 0, v56
	s_nop 1
	v_cndmask_b32_e64 v56, v57, v58, s[36:37]
	v_mul_f32_e32 v57, 0x37800000, v56
	v_cndmask_b32_e32 v56, v56, v57, vcc
	v_cmp_class_f32_e32 vcc, v43, v178
	s_nop 1
	v_cndmask_b32_e32 v43, v56, v43, vcc
	v_mul_f32_e32 v56, 0x3fb8aa3b, v55
	v_rndne_f32_e32 v56, v56
	v_fmamk_f32 v57, v56, 0xbf317218, v55
	v_fmac_f32_e32 v57, 0x3102e308, v56
	v_fmamk_f32 v58, v57, 0x395133b1, v177
	v_cmp_eq_f32_e32 vcc, s2, v56
	v_cvt_i32_f32_e32 v56, v56
	v_fmaak_f32 v58, v57, v58, 0x3c0887f9
	v_fmaak_f32 v58, v57, v58, 0x3d2aaa81
	v_fmaak_f32 v58, v57, v58, 0x3e2aaaab
	v_fma_f32 v58, v57, v58, 0.5
	v_ldexp_f32 v56, 1.0, v56
	v_mul_f32_e32 v58, v57, v58
	v_cndmask_b32_e32 v56, v56, v195, vcc
	v_fmac_f32_e32 v57, v57, v58
	v_add_f32_e32 v58, -1.0, v56
	v_fmac_f32_e32 v58, v56, v57
	v_add_f32_e32 v56, v58, v58
	v_cndmask_b32_e32 v56, v58, v56, vcc
	v_max_f32_e64 v56, -v56, 0
	v_cmp_gt_f32_e32 vcc, s19, v56
	v_mul_f32_e32 v57, 0x4f800000, v56
	s_nop 0
	v_cndmask_b32_e32 v56, v56, v57, vcc
	v_sqrt_f32_e32 v57, v56
	s_nop 0
	v_add_u32_e32 v58, -1, v57
	v_fma_f32 v59, -v58, v57, v56
	v_cmp_ge_f32_e64 s[36:37], 0, v59
	v_add_u32_e32 v59, 1, v57
	s_nop 0
	v_cndmask_b32_e64 v58, v57, v58, s[36:37]
	v_fma_f32 v57, -v59, v57, v56
	v_cmp_lt_f32_e64 s[36:37], 0, v57
	s_nop 1
	v_cndmask_b32_e64 v57, v58, v59, s[36:37]
	v_mul_f32_e32 v58, 0x37800000, v57
	v_cndmask_b32_e32 v57, v57, v58, vcc
	v_cmp_class_f32_e32 vcc, v56, v178
	s_nop 1
	v_cndmask_b32_e32 v56, v57, v56, vcc
	v_cmp_nlt_f32_e32 vcc, s86, v54
	s_nop 1
	v_cndmask_b32_e32 v43, 0, v43, vcc
	v_cmp_nlt_f32_e32 vcc, s86, v55
	s_nop 1
	v_cndmask_b32_e32 v56, 0, v56, vcc
	v_cmp_ngt_f32_e32 vcc, s56, v55
	s_nop 1
	v_cndmask_b32_e32 v55, 1.0, v56, vcc
	v_cmp_ngt_f32_e32 vcc, s56, v54
	s_nop 1
	v_cndmask_b32_e32 v54, 1.0, v43, vcc
	v_pk_mul_f32 v[46:47], v[46:47], v[54:55]
	v_mul_f32_e32 v43, 0x3fb8aa3b, v53
	v_pk_mul_f32 v[46:47], v[46:47], v[50:51]
	v_exp_f32_e32 v43, v43
	v_cvt_pk_bf16_f32 v49, v46, v47
	global_store_dwordx2 v[80:81], v[48:49], off offset:1184
	v_lshl_add_u64 v[48:49], s[26:27], 0, v[60:61]
	v_lshl_add_u64 v[62:63], v[48:49], 0, v[68:69]
	global_load_dwordx4 v[118:121], v[62:63], off
	global_load_dwordx4 v[122:125], v[62:63], off offset:64
	v_lshl_add_u64 v[48:49], s[24:25], 0, v[60:61]
	v_lshl_add_u64 v[64:65], v[48:49], 0, v[68:69]
	global_load_dwordx4 v[126:129], v[64:65], off
	global_load_dwordx4 v[130:133], v[64:65], off offset:64
	ds_read_b128 v[48:51], v87
	s_waitcnt vmcnt(3) lgkmcnt(0)
; #define LAS __attribute__((address_space(3)))
; __device__ __forceinline__ unsigned pk2(float lo, float hi) { return pg8::cvt_pk_bf16(lo, hi); }
; __device__ __forceinline__ float sigmoidf_(float x) { return __builtin_amdgcn_rcpf(1.0f + __expf(-x)); }
; template <bool FULL> __device__ __forceinline__ void lru_tile(const Args& a, int l, int tile, LAS unsigned char* lds, int tid, int lane, int wave) {
;     ...
;         for (int et = 0; et < 8; ++et) {
;             const int e0 = chh * 128 + et * 16, nb = e0 >> 6, el = e0 & 63;
;             f32x4 ra = {0.f, 0.f, 0.f, 0.f}, ia = {0.f, 0.f, 0.f, 0.f};
; #pragma unroll
;             for (int ks = 0; ks < 2; ++ks) {
;                 const bf16x8 xv = *(const LAS bf16x8*)(lds + OFF_XC + ((cb * 16 + fr) * 264 + nb * 64 + 32 * ks + 8 * fq) * 2);
;                 const bf16x8 wa = *(const bf16x8*)(WA + (size_t)nb * 4096 + (el + fr) * 64 + 32 * ks + 8 * fq);
;                 const bf16x8 wx = *(const bf16x8*)(WX + (size_t)nb * 4096 + (el + fr) * 64 + 32 * ks + 8 * fq);
;                 MFMA16(wa, xv, ra); MFMA16(wx, xv, ia);
;             }
;             const int c0 = e0 + 4 * fq;
;             const f32x4 ba = *(const f32x4*)(a.in[22] + (size_t)l * 256 + c0), bx = *(const f32x4*)(a.in[24] + (size_t)l * 256 + c0), c8v = *(const f32x4*)(c8t + c0);
;             const u32x2 xr = *(const LAS u32x2*)(lds + OFF_XC + ((cb * 16 + fr) * 264 + c0) * 2);
;             float lav[4];
;             const float xcv[4] = {__uint_as_float(xr.x << 16), __uint_as_float(xr.x & 0xffff0000u), __uint_as_float(xr.y << 16), __uint_as_float(xr.y & 0xffff0000u)};
; #pragma unroll
;             for (int r = 0; r < 4; ++r) {
;                 const float rg = sigmoidf_(ra[r] + ba[r]), ig = sigmoidf_(ia[r] + bx[r]);
;                 const float la = c8v[r] * rg; const float av_ = __expf(la); const float m2 = -expm1f(2.0f * la);
;                 av[et][r] = av_; bv[et][r] = sqrtf(fmaxf(m2, 0.f)) * ig * xcv[r]; lav[r] = la;
;             }
;             {
;               bf16* yr = Y + (size_t)(t0 + cb * 16 + fr) * DM + c0;
;               u32x2 wl_; wl_.x = pk2(lav[0], lav[1]); wl_.y = pk2(lav[2], lav[3]); *(u32x2*)(yr + 768) = wl_;
;               u32x2 wb_; wb_.x = pk2(bv[et][0], bv[et][1]); wb_.y = pk2(bv[et][2], bv[et][3]); *(u32x2*)(yr + 512) = wb_; }
	v_mfma_f32_16x16x32_bf16 v[52:55], v[118:121], v[48:51], 0
	s_ashr_i32 s24, s5, 6
	s_ashr_i32 s25, s24, 31
	s_lshl_b64 s[24:25], s[24:25], 13
	s_waitcnt vmcnt(1)
	v_mfma_f32_16x16x32_bf16 v[48:51], v[126:129], v[48:51], 0
	ds_read_b128 v[56:59], v87 offset:64
	s_nop 0
	s_add_u32 s26, s57, s24
	s_waitcnt vmcnt(1) lgkmcnt(0)
	v_mfma_f32_16x16x32_bf16 v[60:63], v[122:125], v[56:59], v[52:55]
	s_addc_u32 s27, s58, s25
	s_add_u32 s24, s59, s24
	s_addc_u32 s25, s60, s25
	s_waitcnt vmcnt(0)
	v_mfma_f32_16x16x32_bf16 v[52:55], v[130:133], v[56:59], v[48:51]
	global_load_dwordx4 v[64:67], v[72:73], off offset:384
	global_load_dwordx4 v[56:59], v[84:85], off offset:384
	s_nop 0
	global_load_dwordx4 v[48:51], v[82:83], off offset:384
	ds_read_b64 v[74:75], v74
	s_lshl_b32 s1, s1, 14
	s_lshl_b32 s4, s4, 9
	s_add_i32 s1, s1, s4
	s_waitcnt vmcnt(2)
	v_add_f32_e32 v60, v60, v64
	s_waitcnt vmcnt(1)
	v_add_f32_e32 v52, v52, v56
	v_add_f32_e32 v56, v61, v65
	v_mul_f32_e32 v60, 0xbfb8aa3b, v60
	v_mul_f32_e32 v56, 0xbfb8aa3b, v56
	v_exp_f32_e32 v60, v60
	v_exp_f32_e32 v56, v56
	v_add_f32_e32 v53, v53, v57
	s_waitcnt lgkmcnt(0)
	v_lshlrev_b32_e32 v64, 16, v74
	v_add_f32_e32 v60, 1.0, v60
	v_add_f32_e32 v56, 1.0, v56
	v_rcp_f32_e32 v60, v60
	v_rcp_f32_e32 v61, v56
	v_and_b32_e32 v65, 0xffff0000, v74
	v_mul_f32_e32 v52, 0xbfb8aa3b, v52
	v_mul_f32_e32 v53, 0xbfb8aa3b, v53
	s_waitcnt vmcnt(0)
	v_pk_mul_f32 v[56:57], v[48:49], v[60:61]
	v_exp_f32_e32 v52, v52
	v_pk_add_f32 v[60:61], v[56:57], v[56:57]
	v_exp_f32_e32 v53, v53
	v_mul_f32_e32 v49, 0x3fb8aa3b, v60
	v_rndne_f32_e32 v49, v49
	v_fmamk_f32 v74, v49, 0xbf317218, v60
	v_fmac_f32_e32 v74, 0x3102e308, v49
	v_fmamk_f32 v88, v74, 0x395133b1, v177
	v_cmp_eq_f32_e32 vcc, s2, v49
	v_cvt_i32_f32_e32 v49, v49
	v_fmaak_f32 v88, v74, v88, 0x3c0887f9
	v_fmaak_f32 v88, v74, v88, 0x3d2aaa81
	v_fmaak_f32 v88, v74, v88, 0x3e2aaaab
	v_fma_f32 v88, v74, v88, 0.5
	v_ldexp_f32 v49, 1.0, v49
	v_mul_f32_e32 v88, v74, v88
	v_cndmask_b32_e32 v49, v49, v195, vcc
	v_fmac_f32_e32 v74, v74, v88
	v_add_f32_e32 v88, -1.0, v49
	v_fmac_f32_e32 v88, v49, v74
	v_add_f32_e32 v49, v88, v88
	v_cndmask_b32_e32 v49, v88, v49, vcc
	v_max_f32_e64 v49, -v49, 0
	v_cmp_gt_f32_e32 vcc, s19, v49
	v_mul_f32_e32 v74, 0x4f800000, v49
	v_add_f32_e32 v52, 1.0, v52
	v_cndmask_b32_e32 v49, v49, v74, vcc
	v_sqrt_f32_e32 v74, v49
	v_add_f32_e32 v53, 1.0, v53
	v_rcp_f32_e32 v52, v52
	v_rcp_f32_e32 v53, v53
	v_add_u32_e32 v88, -1, v74
	v_fma_f32 v89, -v88, v74, v49
	v_cmp_ge_f32_e64 s[36:37], 0, v89
	v_add_u32_e32 v89, 1, v74
	v_add_f32_e32 v54, v54, v58
	v_cndmask_b32_e64 v88, v74, v88, s[36:37]
	v_fma_f32 v74, -v89, v74, v49
	v_cmp_lt_f32_e64 s[36:37], 0, v74
	v_add_f32_e32 v58, v63, v67
	v_mul_f32_e32 v58, 0xbfb8aa3b, v58
	v_cndmask_b32_e64 v74, v88, v89, s[36:37]
	v_mul_f32_e32 v88, 0x37800000, v74
	v_cndmask_b32_e32 v74, v74, v88, vcc
	v_cmp_class_f32_e32 vcc, v49, v178
	v_exp_f32_e32 v58, v58
	v_add_f32_e32 v55, v55, v59
	v_cndmask_b32_e32 v49, v74, v49, vcc
	v_mul_f32_e32 v74, 0x3fb8aa3b, v61
	v_rndne_f32_e32 v74, v74
	v_fmamk_f32 v88, v74, 0xbf317218, v61
	v_fmac_f32_e32 v88, 0x3102e308, v74
	v_fmamk_f32 v89, v88, 0x395133b1, v177
	v_cmp_eq_f32_e32 vcc, s2, v74
	v_cvt_i32_f32_e32 v74, v74
	v_fmaak_f32 v89, v88, v89, 0x3c0887f9
	v_fmaak_f32 v89, v88, v89, 0x3d2aaa81
	v_fmaak_f32 v89, v88, v89, 0x3e2aaaab
	v_fma_f32 v89, v88, v89, 0.5
	v_ldexp_f32 v74, 1.0, v74
	v_mul_f32_e32 v89, v88, v89
	v_cndmask_b32_e32 v74, v74, v195, vcc
	v_fmac_f32_e32 v88, v88, v89
	v_add_f32_e32 v89, -1.0, v74
	v_fmac_f32_e32 v89, v74, v88
	v_add_f32_e32 v74, v89, v89
	v_cndmask_b32_e32 v74, v89, v74, vcc
	v_max_f32_e64 v74, -v74, 0
	v_cmp_gt_f32_e32 vcc, s19, v74
	v_mul_f32_e32 v88, 0x4f800000, v74
	v_add_f32_e32 v58, 1.0, v58
	v_cndmask_b32_e32 v74, v74, v88, vcc
	v_sqrt_f32_e32 v88, v74
	v_mul_f32_e32 v54, 0xbfb8aa3b, v54
	v_mul_f32_e32 v55, 0xbfb8aa3b, v55
	v_exp_f32_e32 v54, v54
	v_add_u32_e32 v89, -1, v88
	v_fma_f32 v90, -v89, v88, v74
	v_cmp_ge_f32_e64 s[36:37], 0, v90
	v_add_u32_e32 v90, 1, v88
	v_exp_f32_e32 v55, v55
	v_cndmask_b32_e64 v89, v88, v89, s[36:37]
	v_fma_f32 v88, -v90, v88, v74
	v_cmp_lt_f32_e64 s[36:37], 0, v88
	v_add_f32_e32 v54, 1.0, v54
	v_add_f32_e32 v55, 1.0, v55
	v_cndmask_b32_e64 v88, v89, v90, s[36:37]
	v_mul_f32_e32 v89, 0x37800000, v88
	v_cndmask_b32_e32 v88, v88, v89, vcc
	v_cmp_class_f32_e32 vcc, v74, v178
	v_rcp_f32_e32 v54, v54
	v_rcp_f32_e32 v55, v55
	v_cndmask_b32_e32 v74, v88, v74, vcc
	v_cmp_nlt_f32_e32 vcc, s86, v60
	v_mul_f32_e32 v48, 0x3fb8aa3b, v56
	v_and_b32_e32 v59, 0xffff0000, v75
	v_cndmask_b32_e32 v49, 0, v49, vcc
	v_cmp_nlt_f32_e32 vcc, s86, v61
	v_cvt_pk_bf16_f32 v56, v56, v57
	v_exp_f32_e32 v48, v48
	s_nop 0
	v_cndmask_b32_e32 v74, 0, v74, vcc
	v_cmp_ngt_f32_e32 vcc, s56, v61
	s_nop 1
	v_cndmask_b32_e32 v61, 1.0, v74, vcc
	v_cmp_ngt_f32_e32 vcc, s56, v60
	s_nop 1
	v_cndmask_b32_e32 v60, 1.0, v49, vcc
	v_pk_mul_f32 v[52:53], v[52:53], v[60:61]
	v_add_f32_e32 v60, v62, v66
	v_mul_f32_e32 v60, 0xbfb8aa3b, v60
	v_exp_f32_e32 v60, v60
	v_rcp_f32_e32 v61, v58
	v_pk_mul_f32 v[52:53], v[52:53], v[64:65]
	v_mul_f32_e32 v49, 0x3fb8aa3b, v57
	v_add_f32_e32 v60, 1.0, v60
	v_rcp_f32_e32 v60, v60
	v_lshlrev_b32_e32 v58, 16, v75
	v_exp_f32_e32 v49, v49
	v_pk_mul_f32 v[60:61], v[50:51], v[60:61]
	s_nop 0
	v_pk_add_f32 v[62:63], v[60:61], v[60:61]
	v_cvt_pk_bf16_f32 v57, v60, v61
	global_store_dwordx2 v[80:81], v[56:57], off offset:1728
	v_mul_f32_e32 v51, 0x3fb8aa3b, v62
	v_rndne_f32_e32 v51, v51
	v_fmamk_f32 v64, v51, 0xbf317218, v62
	v_fmac_f32_e32 v64, 0x3102e308, v51
	v_fmamk_f32 v65, v64, 0x395133b1, v177
	v_cmp_eq_f32_e32 vcc, s2, v51
; #define LAS __attribute__((address_space(3)))
; __device__ __forceinline__ unsigned pk2(float lo, float hi) { return pg8::cvt_pk_bf16(lo, hi); }
; __device__ __forceinline__ float sigmoidf_(float x) { return __builtin_amdgcn_rcpf(1.0f + __expf(-x)); }
; template <bool FULL> __device__ __forceinline__ void lru_tile(const Args& a, int l, int tile, LAS unsigned char* lds, int tid, int lane, int wave) {
;     ...
;         for (int et = 0; et < 8; ++et) {
;             const int e0 = chh * 128 + et * 16, nb = e0 >> 6, el = e0 & 63;
;             f32x4 ra = {0.f, 0.f, 0.f, 0.f}, ia = {0.f, 0.f, 0.f, 0.f};
; #pragma unroll
;             for (int ks = 0; ks < 2; ++ks) {
;                 const bf16x8 xv = *(const LAS bf16x8*)(lds + OFF_XC + ((cb * 16 + fr) * 264 + nb * 64 + 32 * ks + 8 * fq) * 2);
;                 const bf16x8 wa = *(const bf16x8*)(WA + (size_t)nb * 4096 + (el + fr) * 64 + 32 * ks + 8 * fq);
;                 const bf16x8 wx = *(const bf16x8*)(WX + (size_t)nb * 4096 + (el + fr) * 64 + 32 * ks + 8 * fq);
;                 MFMA16(wa, xv, ra); MFMA16(wx, xv, ia);
;             }
;             const int c0 = e0 + 4 * fq;
;             const f32x4 ba = *(const f32x4*)(a.in[22] + (size_t)l * 256 + c0), bx = *(const f32x4*)(a.in[24] + (size_t)l * 256 + c0), c8v = *(const f32x4*)(c8t + c0);
;             const u32x2 xr = *(const LAS u32x2*)(lds + OFF_XC + ((cb * 16 + fr) * 264 + c0) * 2);
;             float lav[4];
;             const float xcv[4] = {__uint_as_float(xr.x << 16), __uint_as_float(xr.x & 0xffff0000u), __uint_as_float(xr.y << 16), __uint_as_float(xr.y & 0xffff0000u)};
; #pragma unroll
;             for (int r = 0; r < 4; ++r) {
;                 const float rg = sigmoidf_(ra[r] + ba[r]), ig = sigmoidf_(ia[r] + bx[r]);
;                 const float la = c8v[r] * rg; const float av_ = __expf(la); const float m2 = -expm1f(2.0f * la);
;                 av[et][r] = av_; bv[et][r] = sqrtf(fmaxf(m2, 0.f)) * ig * xcv[r]; lav[r] = la;
;             }
;             {
;               bf16* yr = Y + (size_t)(t0 + cb * 16 + fr) * DM + c0;
;               u32x2 wl_; wl_.x = pk2(lav[0], lav[1]); wl_.y = pk2(lav[2], lav[3]); *(u32x2*)(yr + 768) = wl_;
;               u32x2 wb_; wb_.x = pk2(bv[et][0], bv[et][1]); wb_.y = pk2(bv[et][2], bv[et][3]); *(u32x2*)(yr + 512) = wb_; }
	v_cvt_i32_f32_e32 v51, v51
	v_fmaak_f32 v65, v64, v65, 0x3c0887f9
	v_fmaak_f32 v65, v64, v65, 0x3d2aaa81
	v_fmaak_f32 v65, v64, v65, 0x3e2aaaab
	v_fma_f32 v65, v64, v65, 0.5
	v_ldexp_f32 v51, 1.0, v51
	v_mul_f32_e32 v65, v64, v65
	v_cndmask_b32_e32 v51, v51, v195, vcc
	v_fmac_f32_e32 v64, v64, v65
	v_add_f32_e32 v65, -1.0, v51
	v_fmac_f32_e32 v65, v51, v64
	v_add_f32_e32 v51, v65, v65
	v_cndmask_b32_e32 v51, v65, v51, vcc
	v_max_f32_e64 v51, -v51, 0
	v_cmp_gt_f32_e32 vcc, s19, v51
	v_mul_f32_e32 v64, 0x4f800000, v51
	v_cvt_pk_bf16_f32 v56, v52, v53
	v_mul_f32_e32 v50, 0x3fb8aa3b, v60
	v_cndmask_b32_e32 v51, v51, v64, vcc
	v_sqrt_f32_e32 v64, v51
	v_exp_f32_e32 v50, v50
	v_add_u32_e32 v65, -1, v64
	v_fma_f32 v66, -v65, v64, v51
	v_cmp_ge_f32_e64 s[36:37], 0, v66
	v_add_u32_e32 v66, 1, v64
	s_nop 0
	v_cndmask_b32_e64 v65, v64, v65, s[36:37]
	v_fma_f32 v64, -v66, v64, v51
	v_cmp_lt_f32_e64 s[36:37], 0, v64
	s_nop 1
	v_cndmask_b32_e64 v64, v65, v66, s[36:37]
	v_mul_f32_e32 v65, 0x37800000, v64
	v_cndmask_b32_e32 v64, v64, v65, vcc
	v_cmp_class_f32_e32 vcc, v51, v178
	s_nop 1
	v_cndmask_b32_e32 v51, v64, v51, vcc
	v_mul_f32_e32 v64, 0x3fb8aa3b, v63
	v_rndne_f32_e32 v64, v64
	v_fmamk_f32 v65, v64, 0xbf317218, v63
	v_fmac_f32_e32 v65, 0x3102e308, v64
	v_fmamk_f32 v66, v65, 0x395133b1, v177
	v_cmp_eq_f32_e32 vcc, s2, v64
	v_cvt_i32_f32_e32 v64, v64
	v_fmaak_f32 v66, v65, v66, 0x3c0887f9
	v_fmaak_f32 v66, v65, v66, 0x3d2aaa81
	v_fmaak_f32 v66, v65, v66, 0x3e2aaaab
	v_fma_f32 v66, v65, v66, 0.5
	v_ldexp_f32 v64, 1.0, v64
	v_mul_f32_e32 v66, v65, v66
	v_cndmask_b32_e32 v64, v64, v195, vcc
	v_fmac_f32_e32 v65, v65, v66
	v_add_f32_e32 v66, -1.0, v64
	v_fmac_f32_e32 v66, v64, v65
	v_add_f32_e32 v64, v66, v66
	v_cndmask_b32_e32 v64, v66, v64, vcc
	v_max_f32_e64 v64, -v64, 0
	v_cmp_gt_f32_e32 vcc, s19, v64
	v_mul_f32_e32 v65, 0x4f800000, v64
	s_nop 0
	v_cndmask_b32_e32 v64, v64, v65, vcc
	v_sqrt_f32_e32 v65, v64
	s_nop 0
	v_add_u32_e32 v66, -1, v65
	v_fma_f32 v67, -v66, v65, v64
	v_cmp_ge_f32_e64 s[36:37], 0, v67
	v_add_u32_e32 v67, 1, v65
	s_nop 0
	v_cndmask_b32_e64 v66, v65, v66, s[36:37]
	v_fma_f32 v65, -v67, v65, v64
	v_cmp_lt_f32_e64 s[36:37], 0, v65
	s_nop 1
	v_cndmask_b32_e64 v65, v66, v67, s[36:37]
	v_mul_f32_e32 v66, 0x37800000, v65
	v_cndmask_b32_e32 v65, v65, v66, vcc
	v_cmp_class_f32_e32 vcc, v64, v178
	s_nop 1
	v_cndmask_b32_e32 v64, v65, v64, vcc
	v_cmp_nlt_f32_e32 vcc, s86, v62
	s_nop 1
	v_cndmask_b32_e32 v51, 0, v51, vcc
	v_cmp_nlt_f32_e32 vcc, s86, v63
	s_nop 1
	v_cndmask_b32_e32 v64, 0, v64, vcc
	v_cmp_ngt_f32_e32 vcc, s56, v63
	s_nop 1
	v_cndmask_b32_e32 v63, 1.0, v64, vcc
	v_cmp_ngt_f32_e32 vcc, s56, v62
	s_nop 1
	v_cndmask_b32_e32 v62, 1.0, v51, vcc
	v_pk_mul_f32 v[54:55], v[54:55], v[62:63]
	v_mul_f32_e32 v51, 0x3fb8aa3b, v61
	v_pk_mul_f32 v[54:55], v[54:55], v[58:59]
	v_exp_f32_e32 v51, v51
	v_cvt_pk_bf16_f32 v57, v54, v55
	global_store_dwordx2 v[80:81], v[56:57], off offset:1216
	v_lshl_add_u64 v[56:57], s[26:27], 0, v[70:71]
	v_lshl_add_u64 v[74:75], v[56:57], 0, v[68:69]
	global_load_dwordx4 v[118:121], v[74:75], off
	global_load_dwordx4 v[122:125], v[74:75], off offset:64
	v_lshl_add_u64 v[56:57], s[24:25], 0, v[70:71]
	v_lshl_add_u64 v[88:89], v[56:57], 0, v[68:69]
	global_load_dwordx4 v[126:129], v[88:89], off
	ds_read_b128 v[56:59], v87
	global_load_dwordx4 v[88:91], v[88:89], off offset:64
	s_waitcnt vmcnt(3) lgkmcnt(0)
	v_mfma_f32_16x16x32_bf16 v[60:63], v[118:121], v[56:59], 0
	s_waitcnt vmcnt(1)
	v_mfma_f32_16x16x32_bf16 v[56:59], v[126:129], v[56:59], 0
	ds_read_b128 v[64:67], v87 offset:64
	global_load_dwordx4 v[72:75], v[72:73], off offset:448
	s_nop 0
	s_waitcnt vmcnt(2) lgkmcnt(0)
	v_mfma_f32_16x16x32_bf16 v[60:63], v[122:125], v[64:67], v[60:63]
	s_waitcnt vmcnt(1)
	v_mfma_f32_16x16x32_bf16 v[56:59], v[88:91], v[64:67], v[56:59]
	s_nop 0
	global_load_dwordx4 v[64:67], v[84:85], off offset:448
	global_load_dwordx4 v[68:71], v[82:83], off offset:448
	ds_read_b64 v[82:83], v79
	s_waitcnt lgkmcnt(0)
	v_lshlrev_b32_e32 v84, 16, v82
	v_and_b32_e32 v85, 0xffff0000, v82
	s_waitcnt vmcnt(2)
	v_add_f32_e32 v60, v60, v72
	s_waitcnt vmcnt(1)
	v_add_f32_e32 v56, v56, v64
	v_mul_f32_e32 v60, 0xbfb8aa3b, v60
	v_mul_f32_e32 v56, 0xbfb8aa3b, v56
	v_exp_f32_e32 v60, v60
	v_exp_f32_e32 v56, v56
	v_add_f32_e32 v62, v62, v74
	v_add_f32_e32 v58, v58, v66
	v_add_f32_e32 v60, 1.0, v60
	v_add_f32_e32 v56, 1.0, v56
	v_rcp_f32_e32 v72, v60
	v_rcp_f32_e32 v60, v56
	v_add_f32_e32 v56, v61, v73
	v_mul_f32_e32 v56, 0xbfb8aa3b, v56
	v_exp_f32_e32 v56, v56
	v_mul_f32_e32 v62, 0xbfb8aa3b, v62
	v_mul_f32_e32 v58, 0xbfb8aa3b, v58
	v_exp_f32_e32 v62, v62
	v_add_f32_e32 v56, 1.0, v56
	v_rcp_f32_e32 v73, v56
	v_add_f32_e32 v56, v57, v65
	v_mul_f32_e32 v56, 0xbfb8aa3b, v56
	v_exp_f32_e32 v56, v56
	s_waitcnt vmcnt(0)
; #define LAS __attribute__((address_space(3)))
; __device__ __forceinline__ unsigned pk2(float lo, float hi) { return pg8::cvt_pk_bf16(lo, hi); }
; __device__ __forceinline__ float sigmoidf_(float x) { return __builtin_amdgcn_rcpf(1.0f + __expf(-x)); }
; template <bool FULL> __device__ __forceinline__ void lru_tile(const Args& a, int l, int tile, LAS unsigned char* lds, int tid, int lane, int wave) {
;     ...
;         for (int et = 0; et < 8; ++et) {
;             const int e0 = chh * 128 + et * 16, nb = e0 >> 6, el = e0 & 63;
;             f32x4 ra = {0.f, 0.f, 0.f, 0.f}, ia = {0.f, 0.f, 0.f, 0.f};
; #pragma unroll
;             for (int ks = 0; ks < 2; ++ks) {
;                 const bf16x8 xv = *(const LAS bf16x8*)(lds + OFF_XC + ((cb * 16 + fr) * 264 + nb * 64 + 32 * ks + 8 * fq) * 2);
;                 const bf16x8 wa = *(const bf16x8*)(WA + (size_t)nb * 4096 + (el + fr) * 64 + 32 * ks + 8 * fq);
;                 const bf16x8 wx = *(const bf16x8*)(WX + (size_t)nb * 4096 + (el + fr) * 64 + 32 * ks + 8 * fq);
;                 MFMA16(wa, xv, ra); MFMA16(wx, xv, ia);
;             }
;             const int c0 = e0 + 4 * fq;
;             const f32x4 ba = *(const f32x4*)(a.in[22] + (size_t)l * 256 + c0), bx = *(const f32x4*)(a.in[24] + (size_t)l * 256 + c0), c8v = *(const f32x4*)(c8t + c0);
;             const u32x2 xr = *(const LAS u32x2*)(lds + OFF_XC + ((cb * 16 + fr) * 264 + c0) * 2);
;             float lav[4];
;             const float xcv[4] = {__uint_as_float(xr.x << 16), __uint_as_float(xr.x & 0xffff0000u), __uint_as_float(xr.y << 16), __uint_as_float(xr.y & 0xffff0000u)};
; #pragma unroll
;             for (int r = 0; r < 4; ++r) {
;                 const float rg = sigmoidf_(ra[r] + ba[r]), ig = sigmoidf_(ia[r] + bx[r]);
;                 const float la = c8v[r] * rg; const float av_ = __expf(la); const float m2 = -expm1f(2.0f * la);
;                 av[et][r] = av_; bv[et][r] = sqrtf(fmaxf(m2, 0.f)) * ig * xcv[r]; lav[r] = la;
;             }
;             {
;               bf16* yr = Y + (size_t)(t0 + cb * 16 + fr) * DM + c0;
;               u32x2 wl_; wl_.x = pk2(lav[0], lav[1]); wl_.y = pk2(lav[2], lav[3]); *(u32x2*)(yr + 768) = wl_;
;               u32x2 wb_; wb_.x = pk2(bv[et][0], bv[et][1]); wb_.y = pk2(bv[et][2], bv[et][3]); *(u32x2*)(yr + 512) = wb_; }
	v_pk_mul_f32 v[64:65], v[68:69], v[72:73]
	v_exp_f32_e32 v58, v58
	v_pk_add_f32 v[68:69], v[64:65], v[64:65]
	v_add_f32_e32 v56, 1.0, v56
	v_mul_f32_e32 v57, 0x3fb8aa3b, v68
	v_rndne_f32_e32 v57, v57
	v_fmamk_f32 v72, v57, 0xbf317218, v68
	v_fmac_f32_e32 v72, 0x3102e308, v57
	v_fmamk_f32 v73, v72, 0x395133b1, v177
	v_cmp_eq_f32_e32 vcc, s2, v57
	v_cvt_i32_f32_e32 v57, v57
	v_fmaak_f32 v73, v72, v73, 0x3c0887f9
	v_fmaak_f32 v73, v72, v73, 0x3d2aaa81
	v_fmaak_f32 v73, v72, v73, 0x3e2aaaab
	v_fma_f32 v73, v72, v73, 0.5
	v_ldexp_f32 v57, 1.0, v57
	v_mul_f32_e32 v73, v72, v73
	v_cndmask_b32_e32 v57, v57, v195, vcc
	v_fmac_f32_e32 v72, v72, v73
	v_add_f32_e32 v73, -1.0, v57
	v_fmac_f32_e32 v73, v57, v72
	v_add_f32_e32 v57, v73, v73
	v_cndmask_b32_e32 v57, v73, v57, vcc
	v_max_f32_e64 v57, -v57, 0
	v_cmp_gt_f32_e32 vcc, s19, v57
	v_mul_f32_e32 v72, 0x4f800000, v57
	v_rcp_f32_e32 v61, v56
	v_cndmask_b32_e32 v57, v57, v72, vcc
	v_sqrt_f32_e32 v72, v57
	v_add_f32_e32 v62, 1.0, v62
	v_add_f32_e32 v58, 1.0, v58
	v_mul_f32_e32 v56, 0x3fb8aa3b, v64
	v_add_u32_e32 v73, -1, v72
	v_fma_f32 v79, -v73, v72, v57
	v_cmp_ge_f32_e64 s[36:37], 0, v79
	v_add_u32_e32 v79, 1, v72
	v_cvt_pk_bf16_f32 v64, v64, v65
	v_lshlrev_b32_e32 v66, 16, v83
	v_cndmask_b32_e64 v73, v72, v73, s[36:37]
	v_fma_f32 v72, -v79, v72, v57
	v_cmp_lt_f32_e64 s[36:37], 0, v72
	v_exp_f32_e32 v56, v56
	s_nop 0
	v_cndmask_b32_e64 v72, v73, v79, s[36:37]
	v_mul_f32_e32 v73, 0x37800000, v72
	v_cndmask_b32_e32 v72, v72, v73, vcc
	v_cmp_class_f32_e32 vcc, v57, v178
	s_nop 1
	v_cndmask_b32_e32 v57, v72, v57, vcc
	v_mul_f32_e32 v72, 0x3fb8aa3b, v69
	v_rndne_f32_e32 v72, v72
	v_fmamk_f32 v73, v72, 0xbf317218, v69
	v_fmac_f32_e32 v73, 0x3102e308, v72
	v_fmamk_f32 v79, v73, 0x395133b1, v177
	v_cmp_eq_f32_e32 vcc, s2, v72
	v_cvt_i32_f32_e32 v72, v72
	v_fmaak_f32 v79, v73, v79, 0x3c0887f9
	v_fmaak_f32 v79, v73, v79, 0x3d2aaa81
	v_fmaak_f32 v79, v73, v79, 0x3e2aaaab
	v_fma_f32 v79, v73, v79, 0.5
	v_ldexp_f32 v72, 1.0, v72
	v_mul_f32_e32 v79, v73, v79
	v_cndmask_b32_e32 v72, v72, v195, vcc
	v_fmac_f32_e32 v73, v73, v79
	v_add_f32_e32 v79, -1.0, v72
	v_fmac_f32_e32 v79, v72, v73
	v_add_f32_e32 v72, v79, v79
	v_cndmask_b32_e32 v72, v79, v72, vcc
	v_max_f32_e64 v72, -v72, 0
	v_cmp_gt_f32_e32 vcc, s19, v72
	v_mul_f32_e32 v73, 0x4f800000, v72
	s_nop 0
	v_cndmask_b32_e32 v72, v72, v73, vcc
	v_sqrt_f32_e32 v73, v72
	s_nop 0
	v_add_u32_e32 v79, -1, v73
	v_fma_f32 v82, -v79, v73, v72
	v_cmp_ge_f32_e64 s[36:37], 0, v82
	v_add_u32_e32 v82, 1, v73
	s_nop 0
	v_cndmask_b32_e64 v79, v73, v79, s[36:37]
	v_fma_f32 v73, -v82, v73, v72
	v_cmp_lt_f32_e64 s[36:37], 0, v73
	s_nop 1
	v_cndmask_b32_e64 v73, v79, v82, s[36:37]
	v_mul_f32_e32 v79, 0x37800000, v73
	v_cndmask_b32_e32 v73, v73, v79, vcc
	v_cmp_class_f32_e32 vcc, v72, v178
	s_nop 1
	v_cndmask_b32_e32 v72, v73, v72, vcc
	v_cmp_nlt_f32_e32 vcc, s86, v68
	s_nop 1
	v_cndmask_b32_e32 v57, 0, v57, vcc
	v_cmp_nlt_f32_e32 vcc, s86, v69
	s_nop 1
	v_cndmask_b32_e32 v72, 0, v72, vcc
	v_cmp_ngt_f32_e32 vcc, s56, v69
	s_nop 1
	v_cndmask_b32_e32 v69, 1.0, v72, vcc
	v_cmp_ngt_f32_e32 vcc, s56, v68
	s_nop 1
	v_cndmask_b32_e32 v68, 1.0, v57, vcc
	v_pk_mul_f32 v[60:61], v[60:61], v[68:69]
	v_rcp_f32_e32 v68, v62
	v_rcp_f32_e32 v62, v58
	v_add_f32_e32 v58, v63, v75
	v_mul_f32_e32 v58, 0xbfb8aa3b, v58
	v_exp_f32_e32 v58, v58
	v_pk_mul_f32 v[60:61], v[60:61], v[84:85]
	v_mul_f32_e32 v57, 0x3fb8aa3b, v65
	v_exp_f32_e32 v57, v57
	v_add_f32_e32 v58, 1.0, v58
	v_rcp_f32_e32 v69, v58
	v_add_f32_e32 v58, v59, v67
	v_mul_f32_e32 v58, 0xbfb8aa3b, v58
	v_exp_f32_e32 v58, v58
	v_pk_mul_f32 v[68:69], v[70:71], v[68:69]
	v_and_b32_e32 v67, 0xffff0000, v83
	v_pk_add_f32 v[70:71], v[68:69], v[68:69]
	v_add_f32_e32 v58, 1.0, v58
	v_mul_f32_e32 v59, 0x3fb8aa3b, v70
	v_rndne_f32_e32 v59, v59
	v_fmamk_f32 v72, v59, 0xbf317218, v70
	v_fmac_f32_e32 v72, 0x3102e308, v59
	v_fmamk_f32 v73, v72, 0x395133b1, v177
	v_cmp_eq_f32_e32 vcc, s2, v59
	v_cvt_i32_f32_e32 v59, v59
	v_fmaak_f32 v73, v72, v73, 0x3c0887f9
	v_fmaak_f32 v73, v72, v73, 0x3d2aaa81
	v_fmaak_f32 v73, v72, v73, 0x3e2aaaab
	v_fma_f32 v73, v72, v73, 0.5
	v_ldexp_f32 v59, 1.0, v59
	v_mul_f32_e32 v73, v72, v73
	v_cndmask_b32_e32 v59, v59, v195, vcc
	v_fmac_f32_e32 v72, v72, v73
	v_add_f32_e32 v73, -1.0, v59
	v_fmac_f32_e32 v73, v59, v72
	v_add_f32_e32 v59, v73, v73
	v_cndmask_b32_e32 v59, v73, v59, vcc
	v_max_f32_e64 v59, -v59, 0
	v_cmp_gt_f32_e32 vcc, s19, v59
	v_mul_f32_e32 v72, 0x4f800000, v59
	v_rcp_f32_e32 v63, v58
	v_cndmask_b32_e32 v59, v59, v72, vcc
	v_sqrt_f32_e32 v72, v59
	v_cvt_pk_bf16_f32 v65, v68, v69
	global_store_dwordx2 v[80:81], v[64:65], off offset:1760
	v_cvt_pk_bf16_f32 v64, v60, v61
	v_add_u32_e32 v73, -1, v72
	v_fma_f32 v74, -v73, v72, v59
	v_cmp_ge_f32_e64 s[36:37], 0, v74
	v_add_u32_e32 v74, 1, v72
	v_mul_f32_e32 v58, 0x3fb8aa3b, v68
	v_cndmask_b32_e64 v73, v72, v73, s[36:37]
	v_fma_f32 v72, -v74, v72, v59
	v_cmp_lt_f32_e64 s[36:37], 0, v72
	v_exp_f32_e32 v58, v58
	s_nop 0
	v_cndmask_b32_e64 v72, v73, v74, s[36:37]
	v_mul_f32_e32 v73, 0x37800000, v72
	v_cndmask_b32_e32 v72, v72, v73, vcc
	v_cmp_class_f32_e32 vcc, v59, v178
	s_nop 1
	v_cndmask_b32_e32 v59, v72, v59, vcc
	v_mul_f32_e32 v72, 0x3fb8aa3b, v71
	v_rndne_f32_e32 v72, v72
	v_fmamk_f32 v73, v72, 0xbf317218, v71
	v_fmac_f32_e32 v73, 0x3102e308, v72
	v_fmamk_f32 v74, v73, 0x395133b1, v177
	v_cmp_eq_f32_e32 vcc, s2, v72
	v_cvt_i32_f32_e32 v72, v72
	v_fmaak_f32 v74, v73, v74, 0x3c0887f9
	v_fmaak_f32 v74, v73, v74, 0x3d2aaa81
	v_fmaak_f32 v74, v73, v74, 0x3e2aaaab
	v_fma_f32 v74, v73, v74, 0.5
	v_ldexp_f32 v72, 1.0, v72
	v_mul_f32_e32 v74, v73, v74
	v_cndmask_b32_e32 v72, v72, v195, vcc
; #define LAS __attribute__((address_space(3)))
; __device__ __forceinline__ unsigned pk2(float lo, float hi) { return pg8::cvt_pk_bf16(lo, hi); }
; template <bool FULL> __device__ __forceinline__ void lru_tile(const Args& a, int l, int tile, LAS unsigned char* lds, int tid, int lane, int wave) {
;     ...
;               bf16* yr = Y + (size_t)(t0 + cb * 16 + fr) * DM + c0;
;               u32x2 wl_; wl_.x = pk2(lav[0], lav[1]); wl_.y = pk2(lav[2], lav[3]); *(u32x2*)(yr + 768) = wl_;
;               u32x2 wb_; wb_.x = pk2(bv[et][0], bv[et][1]); wb_.y = pk2(bv[et][2], bv[et][3]); *(u32x2*)(yr + 512) = wb_; }
;             if ((et & 3) == 3) asm volatile("" ::: "memory");
;         }
;         __syncthreads();
; #pragma unroll
;         for (int et = 0; et < 8; ++et) { const int c0 = chh * 128 + et * 16 + 4 * fq, t = cb * 16 + fr;
;             *(LAS f32x4*)(lds + OFF_LA + (t * 256 + c0) * 4) = av[et]; *(LAS f32x4*)(lds + OFF_LB + (t * 256 + c0) * 4) = bv[et]; }
;     }
;     }
;     __syncthreads();
;     float* AE = (float*)(a.ws + WS_LRUC); float* HE = AE + 2 * 128 * 256;
;     if (tid < 256) {
;         LAS float* A = (LAS float*)(lds + OFF_LA) + tid; LAS float* B = (LAS float*)(lds + OFF_LB) + tid;
;         float h = FULL ? HE[(size_t)tile * 256 + tid] : 0.f, P = 1.f;
;         for (int tb = 0; tb < 64; tb += 16) {
;             float av_[16], bv_[16];
; #pragma unroll
;             for (int j = 0; j < 16; ++j) { av_[j] = A[(tb + j) * 256]; bv_[j] = B[(tb + j) * 256]; }
; #pragma unroll
;             for (int j = 0; j < 16; ++j) { h = fmaf(av_[j], h, bv_[j]); if (FULL) bv_[j] = h; else P *= av_[j]; }
;             if (FULL) {
; #pragma unroll
;                 for (int j = 0; j < 16; ++j) B[(tb + j) * 256] = bv_[j];
;             }
;         }
	v_fmac_f32_e32 v73, v73, v74
	v_add_f32_e32 v74, -1.0, v72
	v_fmac_f32_e32 v74, v72, v73
	v_add_f32_e32 v72, v74, v74
	v_cndmask_b32_e32 v72, v74, v72, vcc
	v_max_f32_e64 v72, -v72, 0
	v_cmp_gt_f32_e32 vcc, s19, v72
	v_mul_f32_e32 v73, 0x4f800000, v72
	s_nop 0
	v_cndmask_b32_e32 v72, v72, v73, vcc
	v_sqrt_f32_e32 v73, v72
	s_nop 0
	v_add_u32_e32 v74, -1, v73
	v_fma_f32 v75, -v74, v73, v72
	v_cmp_ge_f32_e64 s[36:37], 0, v75
	v_add_u32_e32 v75, 1, v73
	s_nop 0
	v_cndmask_b32_e64 v74, v73, v74, s[36:37]
	v_fma_f32 v73, -v75, v73, v72
	v_cmp_lt_f32_e64 s[36:37], 0, v73
	s_nop 1
	v_cndmask_b32_e64 v73, v74, v75, s[36:37]
	v_mul_f32_e32 v74, 0x37800000, v73
	v_cndmask_b32_e32 v73, v73, v74, vcc
	v_cmp_class_f32_e32 vcc, v72, v178
	s_nop 1
	v_cndmask_b32_e32 v72, v73, v72, vcc
	v_cmp_nlt_f32_e32 vcc, s86, v70
	s_nop 1
	v_cndmask_b32_e32 v59, 0, v59, vcc
	v_cmp_nlt_f32_e32 vcc, s86, v71
	s_nop 1
	v_cndmask_b32_e32 v72, 0, v72, vcc
	v_cmp_ngt_f32_e32 vcc, s56, v71
	s_nop 1
	v_cndmask_b32_e32 v71, 1.0, v72, vcc
	v_cmp_ngt_f32_e32 vcc, s56, v70
	s_nop 1
	v_cndmask_b32_e32 v70, 1.0, v59, vcc
	v_pk_mul_f32 v[62:63], v[62:63], v[70:71]
	v_mul_f32_e32 v59, 0x3fb8aa3b, v69
	v_pk_mul_f32 v[62:63], v[62:63], v[66:67]
	v_exp_f32_e32 v59, v59
	v_cvt_pk_bf16_f32 v65, v62, v63
	global_store_dwordx2 v[80:81], v[64:65], off offset:1248
	v_lshl_or_b32 v64, v77, 10, v78
	v_add_u32_e32 v64, s1, v64
	v_add_u32_e32 v65, 0, v64
	s_barrier
	ds_write_b128 v65, v[0:3]
	v_add_u32_e32 v0, s0, v64
	s_movk_i32 s0, 0x100
	v_cmp_gt_i32_e32 vcc, s0, v76
	ds_write_b128 v0, v[4:7]
	ds_write_b128 v65, v[8:11] offset:64
	ds_write_b128 v0, v[12:15] offset:64
	ds_write_b128 v65, v[16:19] offset:128
	ds_write_b128 v0, v[20:23] offset:128
	ds_write_b128 v65, v[24:27] offset:192
	ds_write_b128 v0, v[28:31] offset:192
	ds_write_b128 v65, v[32:35] offset:256
	ds_write_b128 v0, v[36:39] offset:256
	ds_write_b128 v65, v[40:43] offset:320
	ds_write_b128 v0, v[44:47] offset:320
	ds_write_b128 v65, v[48:51] offset:384
	ds_write_b128 v0, v[52:55] offset:384
	ds_write_b128 v65, v[56:59] offset:448
	ds_write_b128 v0, v[60:63] offset:448
	s_waitcnt lgkmcnt(0)
	s_barrier
	s_and_saveexec_b64 s[0:1], vcc
	s_cbranch_execz .LBB0_1256
	v_lshl_add_u32 v34, v76, 2, 0
	v_add_u32_e32 v35, 0x10000, v34
	ds_read2st64_b32 v[0:1], v34 offset1:4
	ds_read2st64_b32 v[2:3], v35 offset1:4
	ds_read2st64_b32 v[4:5], v34 offset0:8 offset1:12
	ds_read2st64_b32 v[6:7], v35 offset0:8 offset1:12
	ds_read2st64_b32 v[8:9], v34 offset0:16 offset1:20
	ds_read2st64_b32 v[10:11], v35 offset0:16 offset1:20
	ds_read2st64_b32 v[12:13], v34 offset0:24 offset1:28
	ds_read2st64_b32 v[14:15], v35 offset0:24 offset1:28
	ds_read2st64_b32 v[16:17], v34 offset0:32 offset1:36
	ds_read2st64_b32 v[18:19], v35 offset0:32 offset1:36
	ds_read2st64_b32 v[20:21], v34 offset0:40 offset1:44
	ds_read2st64_b32 v[22:23], v35 offset0:40 offset1:44
	ds_read2st64_b32 v[24:25], v34 offset0:48 offset1:52
	ds_read2st64_b32 v[26:27], v35 offset0:48 offset1:52
	ds_read2st64_b32 v[28:29], v34 offset0:56 offset1:60
	ds_read2st64_b32 v[30:31], v35 offset0:56 offset1:60
	s_waitcnt lgkmcnt(14)
	v_fma_f32 v2, 0, v0, v2
	v_fmac_f32_e32 v3, v1, v2
	v_mul_f32_e32 v0, v0, v1
	s_waitcnt lgkmcnt(12)
	v_fma_f32 v1, v4, v3, v6
	v_mul_f32_e32 v0, v0, v4
	v_fmac_f32_e32 v7, v5, v1
	v_mul_f32_e32 v0, v0, v5
	s_waitcnt lgkmcnt(10)
	v_fma_f32 v1, v8, v7, v10
	v_mul_f32_e32 v0, v0, v8
	v_fmac_f32_e32 v11, v9, v1
	v_mul_f32_e32 v0, v0, v9
	s_waitcnt lgkmcnt(8)
	v_fma_f32 v1, v12, v11, v14
	v_mul_f32_e32 v0, v0, v12
	v_fmac_f32_e32 v15, v13, v1
	v_mul_f32_e32 v0, v0, v13
	s_waitcnt lgkmcnt(6)
	v_fma_f32 v1, v16, v15, v18
	v_mul_f32_e32 v0, v0, v16
	v_fmac_f32_e32 v19, v17, v1
	v_mul_f32_e32 v0, v0, v17
	s_waitcnt lgkmcnt(4)
	v_fma_f32 v1, v20, v19, v22
	v_mul_f32_e32 v0, v0, v20
	v_fmac_f32_e32 v23, v21, v1
	v_mul_f32_e32 v0, v0, v21
	s_waitcnt lgkmcnt(2)
	v_fma_f32 v1, v24, v23, v26
	v_mul_f32_e32 v0, v0, v24
	v_fmac_f32_e32 v27, v25, v1
	v_mul_f32_e32 v0, v0, v25
	s_waitcnt lgkmcnt(0)
	v_fma_f32 v1, v28, v27, v30
	v_mul_f32_e32 v0, v0, v28
	v_fmac_f32_e32 v31, v29, v1
	v_mul_f32_e32 v30, v0, v29
	ds_read2st64_b32 v[0:1], v34 offset0:64 offset1:68
	ds_read2st64_b32 v[2:3], v35 offset0:64 offset1:68
	ds_read2st64_b32 v[4:5], v34 offset0:72 offset1:76
	ds_read2st64_b32 v[6:7], v35 offset0:72 offset1:76
	ds_read2st64_b32 v[8:9], v34 offset0:80 offset1:84
	ds_read2st64_b32 v[10:11], v35 offset0:80 offset1:84
	ds_read2st64_b32 v[12:13], v34 offset0:88 offset1:92
	ds_read2st64_b32 v[14:15], v35 offset0:88 offset1:92
	ds_read2st64_b32 v[16:17], v34 offset0:96 offset1:100
	ds_read2st64_b32 v[18:19], v35 offset0:96 offset1:100
	ds_read2st64_b32 v[20:21], v34 offset0:104 offset1:108
	ds_read2st64_b32 v[22:23], v35 offset0:104 offset1:108
	ds_read2st64_b32 v[24:25], v34 offset0:112 offset1:116
	ds_read2st64_b32 v[26:27], v35 offset0:112 offset1:116
	ds_read2st64_b32 v[28:29], v34 offset0:120 offset1:124
	ds_read2st64_b32 v[32:33], v35 offset0:120 offset1:124
	s_waitcnt lgkmcnt(14)
	v_fma_f32 v2, v0, v31, v2
	v_mul_f32_e32 v0, v30, v0
	v_fmac_f32_e32 v3, v1, v2
	v_mul_f32_e32 v0, v0, v1
	s_waitcnt lgkmcnt(12)
; template <bool FULL> __device__ __forceinline__ void lru_tile(const Args& a, int l, int tile, LAS unsigned char* lds, int tid, int lane, int wave) {
;     ...
;         for (int tb = 0; tb < 64; tb += 16) {
;             float av_[16], bv_[16];
; #pragma unroll
;             for (int j = 0; j < 16; ++j) { av_[j] = A[(tb + j) * 256]; bv_[j] = B[(tb + j) * 256]; }
; #pragma unroll
;             for (int j = 0; j < 16; ++j) { h = fmaf(av_[j], h, bv_[j]); if (FULL) bv_[j] = h; else P *= av_[j]; }
;             if (FULL) {
; #pragma unroll
;                 for (int j = 0; j < 16; ++j) B[(tb + j) * 256] = bv_[j];
;             }
;         }
;         if (!FULL) { AE[(size_t)tile * 256 + tid] = P; HE[(size_t)tile * 256 + tid] = h; }
	v_fma_f32 v1, v4, v3, v6
	v_mul_f32_e32 v0, v0, v4
	v_fmac_f32_e32 v7, v5, v1
	v_mul_f32_e32 v0, v0, v5
	s_waitcnt lgkmcnt(10)
	v_fma_f32 v1, v8, v7, v10
	v_mul_f32_e32 v0, v0, v8
	v_fmac_f32_e32 v11, v9, v1
	v_mul_f32_e32 v0, v0, v9
	s_waitcnt lgkmcnt(8)
	v_fma_f32 v1, v12, v11, v14
	v_mul_f32_e32 v0, v0, v12
	v_fmac_f32_e32 v15, v13, v1
	v_mul_f32_e32 v0, v0, v13
	s_waitcnt lgkmcnt(6)
	v_fma_f32 v1, v16, v15, v18
	v_mul_f32_e32 v0, v0, v16
	v_fmac_f32_e32 v19, v17, v1
	v_mul_f32_e32 v0, v0, v17
	s_waitcnt lgkmcnt(4)
	v_fma_f32 v1, v20, v19, v22
	v_mul_f32_e32 v0, v0, v20
	v_fmac_f32_e32 v23, v21, v1
	v_mul_f32_e32 v0, v0, v21
	s_waitcnt lgkmcnt(2)
	v_fma_f32 v1, v24, v23, v26
	v_mul_f32_e32 v0, v0, v24
	v_fmac_f32_e32 v27, v25, v1
	v_mul_f32_e32 v0, v0, v25
	s_waitcnt lgkmcnt(0)
	v_fma_f32 v1, v28, v27, v32
	v_mul_f32_e32 v0, v0, v28
	v_fmac_f32_e32 v33, v29, v1
	v_mul_f32_e32 v32, v0, v29
	ds_read2st64_b32 v[0:1], v34 offset0:128 offset1:132
	ds_read2st64_b32 v[2:3], v35 offset0:128 offset1:132
	ds_read2st64_b32 v[4:5], v34 offset0:136 offset1:140
	ds_read2st64_b32 v[6:7], v35 offset0:136 offset1:140
	ds_read2st64_b32 v[8:9], v34 offset0:144 offset1:148
	ds_read2st64_b32 v[10:11], v35 offset0:144 offset1:148
	ds_read2st64_b32 v[12:13], v34 offset0:152 offset1:156
	ds_read2st64_b32 v[14:15], v35 offset0:152 offset1:156
	ds_read2st64_b32 v[16:17], v34 offset0:160 offset1:164
	ds_read2st64_b32 v[18:19], v35 offset0:160 offset1:164
	ds_read2st64_b32 v[20:21], v34 offset0:168 offset1:172
	ds_read2st64_b32 v[22:23], v35 offset0:168 offset1:172
	ds_read2st64_b32 v[24:25], v34 offset0:176 offset1:180
	ds_read2st64_b32 v[26:27], v35 offset0:176 offset1:180
	ds_read2st64_b32 v[28:29], v34 offset0:184 offset1:188
	ds_read2st64_b32 v[30:31], v35 offset0:184 offset1:188
	s_waitcnt lgkmcnt(14)
	v_fma_f32 v2, v0, v33, v2
	v_mul_f32_e32 v0, v32, v0
	v_fmac_f32_e32 v3, v1, v2
	v_mul_f32_e32 v0, v0, v1
	s_waitcnt lgkmcnt(12)
	v_fma_f32 v1, v4, v3, v6
	v_mul_f32_e32 v0, v0, v4
	v_fmac_f32_e32 v7, v5, v1
	v_mul_f32_e32 v0, v0, v5
	s_waitcnt lgkmcnt(10)
	v_fma_f32 v1, v8, v7, v10
	v_mul_f32_e32 v0, v0, v8
	v_fmac_f32_e32 v11, v9, v1
	v_mul_f32_e32 v0, v0, v9
	s_waitcnt lgkmcnt(8)
	v_fma_f32 v1, v12, v11, v14
	v_mul_f32_e32 v0, v0, v12
	v_fmac_f32_e32 v15, v13, v1
	v_mul_f32_e32 v0, v0, v13
	s_waitcnt lgkmcnt(6)
	v_fma_f32 v1, v16, v15, v18
	v_mul_f32_e32 v0, v0, v16
	v_fmac_f32_e32 v19, v17, v1
	v_mul_f32_e32 v0, v0, v17
	s_waitcnt lgkmcnt(4)
	v_fma_f32 v1, v20, v19, v22
	v_mul_f32_e32 v0, v0, v20
	v_fmac_f32_e32 v23, v21, v1
	v_mul_f32_e32 v0, v0, v21
	s_waitcnt lgkmcnt(2)
	v_fma_f32 v1, v24, v23, v26
	v_mul_f32_e32 v0, v0, v24
	v_fmac_f32_e32 v27, v25, v1
	v_mul_f32_e32 v0, v0, v25
	s_waitcnt lgkmcnt(0)
	v_fma_f32 v1, v28, v27, v30
	v_mul_f32_e32 v0, v0, v28
	v_fmac_f32_e32 v31, v29, v1
	v_mul_f32_e32 v30, v0, v29
	ds_read2st64_b32 v[0:1], v34 offset0:192 offset1:196
	ds_read2st64_b32 v[2:3], v35 offset0:192 offset1:196
	ds_read2st64_b32 v[4:5], v34 offset0:200 offset1:204
	ds_read2st64_b32 v[6:7], v35 offset0:200 offset1:204
	ds_read2st64_b32 v[8:9], v34 offset0:208 offset1:212
	ds_read2st64_b32 v[10:11], v35 offset0:208 offset1:212
	ds_read2st64_b32 v[12:13], v34 offset0:216 offset1:220
	ds_read2st64_b32 v[14:15], v35 offset0:216 offset1:220
	ds_read2st64_b32 v[16:17], v34 offset0:224 offset1:228
	ds_read2st64_b32 v[18:19], v35 offset0:224 offset1:228
	ds_read2st64_b32 v[20:21], v34 offset0:232 offset1:236
	ds_read2st64_b32 v[22:23], v35 offset0:232 offset1:236
	ds_read2st64_b32 v[24:25], v34 offset0:240 offset1:244
	ds_read2st64_b32 v[26:27], v35 offset0:240 offset1:244
	ds_read2st64_b32 v[28:29], v34 offset0:248 offset1:252
	ds_read2st64_b32 v[32:33], v35 offset0:248 offset1:252
	s_waitcnt lgkmcnt(14)
	v_fma_f32 v2, v0, v31, v2
	v_mul_f32_e32 v0, v30, v0
	v_fmac_f32_e32 v3, v1, v2
	v_mul_f32_e32 v0, v0, v1
	s_waitcnt lgkmcnt(12)
	v_fma_f32 v1, v4, v3, v6
	v_mul_f32_e32 v0, v0, v4
	v_fmac_f32_e32 v7, v5, v1
	v_mul_f32_e32 v0, v0, v5
	s_waitcnt lgkmcnt(10)
	v_fma_f32 v1, v8, v7, v10
	v_mul_f32_e32 v0, v0, v8
	v_fmac_f32_e32 v11, v9, v1
	v_mul_f32_e32 v0, v0, v9
	s_waitcnt lgkmcnt(8)
	v_fma_f32 v1, v12, v11, v14
	v_mul_f32_e32 v0, v0, v12
	v_fmac_f32_e32 v15, v13, v1
	v_mul_f32_e32 v0, v0, v13
	s_waitcnt lgkmcnt(6)
	v_fma_f32 v1, v16, v15, v18
	v_mul_f32_e32 v0, v0, v16
	v_fmac_f32_e32 v19, v17, v1
	v_mul_f32_e32 v0, v0, v17
	s_waitcnt lgkmcnt(4)
	v_fma_f32 v1, v20, v19, v22
	v_mul_f32_e32 v0, v0, v20
	v_fmac_f32_e32 v23, v21, v1
	v_mul_f32_e32 v0, v0, v21
	s_waitcnt lgkmcnt(2)
	v_fma_f32 v1, v24, v23, v26
	v_mul_f32_e32 v0, v0, v24
	v_fmac_f32_e32 v27, v25, v1
	v_mul_f32_e32 v0, v0, v25
	s_ashr_i32 s39, s38, 31
	s_waitcnt lgkmcnt(0)
	v_fma_f32 v1, v28, v27, v32
	v_mul_f32_e32 v0, v0, v28
	s_lshl_b64 s[4:5], s[38:39], 8
	v_ashrrev_i32_e32 v77, 31, v76
	v_fmac_f32_e32 v33, v29, v1
	v_mul_f32_e32 v4, v0, v29
	v_lshl_add_u64 v[0:1], s[4:5], 0, v[76:77]
	v_readlane_b32 s4, v252, 56
	v_lshlrev_b64 v[0:1], 2, v[0:1]
	v_readlane_b32 s5, v252, 57
	s_nop 1
	v_lshl_add_u64 v[2:3], s[4:5], 0, v[0:1]
	v_readlane_b32 s4, v252, 54
	v_readlane_b32 s5, v252, 55
	global_store_dword v[2:3], v4, off sc1
	s_nop 0
	v_lshl_add_u64 v[0:1], s[4:5], 0, v[0:1]
	global_store_dword v[0:1], v33, off sc1
	s_branch .LBB0_1256

; __device__ __forceinline__ unsigned xb_ld(unsigned* p)              { return __hip_atomic_load(p, __ATOMIC_RELAXED, __HIP_MEMORY_SCOPE_AGENT); }
; __device__ __forceinline__ unsigned xb_add(unsigned* p, unsigned v) { return __hip_atomic_fetch_add(p, v, __ATOMIC_RELAXED, __HIP_MEMORY_SCOPE_AGENT); }
; #define XB_SPIN(cond, bar) do { unsigned _sp = 0; while (cond) { __builtin_amdgcn_s_sleep(1); \
;     if ((++_sp & 255u) == 0u) { if (xb_ld(&(bar)[XB_TMO])) break; if (_sp > XB_SPIN_CAP) { atomicAdd(&(bar)[XB_TMO], 1u); break; } } } } while (0)
; __device__ __forceinline__ void xcd_barrier(const XcdBarrier& b) {
;     ...
;         const unsigned old = xb_add(&bar[XB_XSUB(b.x)], 1u);
;         const unsigned gen = old / nloc;
;         if (old + 1u == (gen + 1u) * nloc) {
;             __builtin_amdgcn_fence(__ATOMIC_RELEASE, "agent");
;             asm volatile("s_waitcnt vmcnt(0)" ::: "memory");
;             const unsigned og = xb_add(&bar[XB_TOP], 1u);
;             const unsigned tg = og / nx;
;             if (og + 1u == (tg + 1u) * nx) xb_add(&bar[XB_TOPGEN], 1u);
;             else XB_SPIN(xb_ld(&bar[XB_TOPGEN]) == tg, bar);
;             __builtin_amdgcn_fence(__ATOMIC_ACQUIRE, "agent");
;             xb_add(&bar[XB_XGEN(b.x)], 1u);
;             asm volatile("s_waitcnt vmcnt(0)" ::: "memory");
.LBB0_1354:
	s_andn2_saveexec_b64 s[0:1], s[0:1]
	s_cbranch_execz .LBB0_1374
	s_mov_b64 s[0:1], exec
	s_waitcnt lgkmcnt(0)
	s_waitcnt vmcnt(0)
	v_mbcnt_lo_u32_b32 v1, s0, 0
	v_mbcnt_hi_u32_b32 v1, s1, v1
	v_cmp_eq_u32_e32 vcc, 0, v1
	s_and_saveexec_b64 s[6:7], vcc
	s_cbranch_execz .LBB0_1357
	s_bcnt1_i32_b64 s0, s[0:1]
	v_mov_b32_e32 v2, s0
	v_readlane_b32 s0, v252, 42
	v_readlane_b32 s1, v252, 43
	s_nop 4
	global_atomic_add v2, v145, v2, s[0:1] sc0
